# EpiResid: read-once f32 residual loads (adjacent pairs) issued nt as well as the residual stores
# speedup vs baseline: 1.0053x; 1.0053x over previous
; DEVI void s5_fill(const Params& p) {
;     ...
;     for (int e = gt; e < 64 * 512 * 80; e += nthr) { const int k8 = (e % 80) * 8, n = (e / 80) & 511, g = e / (80 * 512), t = n >> 4, hh = n & 15; float v[8];
;         if (k8 < 512) { const int s = k8 >> 4, h0 = k8 & 15;
; #pragma unroll
;             for (int j = 0; j < 8; ++j) { float x = 0.f; if (s <= t) { x = kc[(((size_t)g * 32 + (t - s)) * 16 + hh) * 16 + h0 + j]; if (s == t && h0 + j == hh) x += p.in[25][g * 16 + hh]; } v[j] = x; }
.LBB0_1017:
	s_mov_b32 s2, 0x66666667
	v_mul_hi_i32 v0, v20, s2
	s_waitcnt lgkmcnt(0)
	v_ashrrev_i32_e32 v1, 5, v0
	v_lshrrev_b32_e32 v2, 31, v0
	v_add_u32_e32 v30, v1, v2
	s_movk_i32 s2, 0xffb0
	v_mad_u64_u32 v[28:29], s[2:3], v30, s2, v[20:21]
	v_ashrrev_i32_e32 v0, 14, v0
	s_movk_i32 s2, 0xfd80
	v_add_u32_e32 v24, v0, v2
	v_mad_u64_u32 v[22:23], s[2:3], v30, s2, v[18:19]
	v_bfe_u32 v26, v30, 4, 5
	v_and_b32_e32 v16, 15, v30
	v_cmp_lt_i32_e32 vcc, 63, v28
	v_ashrrev_i32_e32 v25, 31, v24
	s_mov_b64 s[100:101], exec
	s_mov_b64 s[14:15], 0
	s_andn2_b64 exec, exec, vcc
	s_cbranch_execz .Lbtya_noA
	v_ashrrev_i32_e32 v2, 1, v28
	v_readlane_b32 s2, v252, 40
	v_readlane_b32 s3, v252, 41
	v_sub_u32_e32 v8, v26, v2
	v_lshlrev_b64 v[10:11], 9, v[24:25]
	v_lshl_add_u64 v[0:1], v[8:9], 4, v[10:11]
	v_or_b32_e32 v0, v0, v16
	v_and_b32_e32 v17, 8, v22
	v_lshlrev_b64 v[0:1], 6, v[0:1]
	v_lshlrev_b32_e32 v8, 2, v17
	v_readlane_b32 s38, v251, 42
	v_readlane_b32 s39, v251, 43
	v_lshl_add_u64 v[0:1], s[2:3], 0, v[0:1]
	v_lshl_add_u64 v[12:13], v[0:1], 0, v[8:9]
	v_lshl_or_b32 v0, v24, 4, v16
	v_ashrrev_i32_e32 v1, 31, v0
	v_cmp_ge_i32_e32 vcc, v26, v2
	v_cmp_eq_u32_e64 s[4:5], v26, v2
	v_lshl_add_u64 v[14:15], v[0:1], 2, s[38:39]
	v_and_b32_e32 v8, 8, v16
	v_cmp_eq_u32_e64 s[14:15], v8, v17
	v_mov_b32_e32 v0, 0
	v_mov_b32_e32 v1, 0
	v_mov_b32_e32 v2, 0
	v_mov_b32_e32 v3, 0
	v_mov_b32_e32 v4, 0
	v_mov_b32_e32 v5, 0
	v_mov_b32_e32 v6, 0
	v_mov_b32_e32 v7, 0
	s_and_b64 s[14:15], s[14:15], s[4:5]
	s_and_b64 s[14:15], s[14:15], exec
	s_and_b64 exec, exec, vcc
	global_load_dwordx4 v[0:3], v[12:13], off nt
	global_load_dwordx4 v[4:7], v[12:13], off offset:16 nt
	s_mov_b64 exec, s[14:15]
	global_load_dword v32, v[14:15], off

; DEVI void s5_fill(const Params& p) {
;     ...
;     for (int e = gt; e < 64 * 256 * 64; e += nthr) { const int k8 = (e & 63) * 8, n = (e >> 6) & 255, g = e >> 14, s = k8 >> 4, h0 = k8 & 15; float v[8];
; #pragma unroll
;         for (int j = 0; j < 8; ++j) { float x = 0.f; if (n < 128) { const int pp = n & 63; const size_t gp = (size_t)g * 64 + pp; const float ar = apow[(gp * 34 + 31 - s) * 2], ai = apow[(gp * 34 + 31 - s) * 2 + 1];
;                 const float br = bb[(gp * 16 + h0 + j) * 2], bi = bb[(gp * 16 + h0 + j) * 2 + 1]; x = (n < 64) ? (ar * br - ai * bi) : (ar * bi + ai * br); } v[j] = x; }
.LBB0_1054:
	v_ashrrev_i32_e32 v0, 14, v19
	s_waitcnt lgkmcnt(0)
	v_ashrrev_i32_e32 v1, 31, v0
	v_lshrrev_b32_e32 v2, 6, v19
	v_lshlrev_b64 v[4:5], 6, v[0:1]
	v_bfe_u32 v7, v19, 6, 8
	v_bfe_u32 v8, v6, 4, 5
	s_movk_i32 s0, 0x80
	v_and_or_b32 v4, v2, 63, v4
	v_cmp_gt_u32_e32 vcc, s0, v7
	v_mul_hi_i32_i24_e32 v3, 34, v4
	v_mul_i32_i24_e32 v2, 34, v4
	v_xor_b32_e32 v8, 31, v8
	v_lshlrev_b64 v[4:5], 4, v[4:5]
	v_readlane_b32 s0, v252, 32
	v_lshl_add_u64 v[2:3], v[2:3], 0, v[8:9]
	v_and_or_b32 v4, v6, 8, v4
	v_readlane_b32 s1, v252, 33
	v_lshl_add_u64 v[2:3], v[2:3], 3, s[56:57]
	v_cmp_gt_u32_e64 s[2:3], 64, v7
	v_mov_b32_e32 v8, 0
	v_lshl_add_u64 v[4:5], v[4:5], 3, s[0:1]
	v_mov_b32_e32 v10, 0
	v_mov_b32_e32 v10, 0
	v_mov_b32_e32 v8, 0
	v_mov_b32_e32 v12, 0
	v_mov_b32_e32 v11, 0
	v_mov_b32_e32 v14, 0
	v_mov_b32_e32 v13, 0
	v_mov_b32_e32 v16, 0
	v_mov_b32_e32 v15, 0
	s_and_saveexec_b64 s[8:9], vcc
	s_cbranch_execz .LBB0_1053
	global_load_dwordx2 v[2:3], v[2:3], off
	global_load_dwordx4 v[24:27], v[4:5], off nt
	global_load_dwordx4 v[28:31], v[4:5], off offset:16 nt
	global_load_dwordx4 v[32:35], v[4:5], off offset:32 nt
	global_load_dwordx4 v[36:39], v[4:5], off offset:48 nt
	s_waitcnt vmcnt(0)
	v_pk_mul_f32 v[20:21], v[2:3], v[24:25]
	v_pk_mul_f32 v[22:23], v[2:3], v[24:25] op_sel:[1,0] op_sel_hi:[0,1]
	v_sub_f32_e32 v20, v20, v21
	v_add_f32_e32 v22, v22, v23
	v_cndmask_b32_e64 v10, v22, v20, s[2:3]
	v_pk_mul_f32 v[20:21], v[2:3], v[26:27]
	v_pk_mul_f32 v[22:23], v[2:3], v[26:27] op_sel:[1,0] op_sel_hi:[0,1]
	v_sub_f32_e32 v20, v20, v21
	v_add_f32_e32 v22, v22, v23
	v_cndmask_b32_e64 v8, v22, v20, s[2:3]
	v_pk_mul_f32 v[20:21], v[2:3], v[28:29]
	v_pk_mul_f32 v[22:23], v[2:3], v[28:29] op_sel:[1,0] op_sel_hi:[0,1]
	v_sub_f32_e32 v20, v20, v21
	v_add_f32_e32 v22, v22, v23
	v_cndmask_b32_e64 v12, v22, v20, s[2:3]
	v_pk_mul_f32 v[20:21], v[2:3], v[30:31]
	v_pk_mul_f32 v[22:23], v[2:3], v[30:31] op_sel:[1,0] op_sel_hi:[0,1]
	v_sub_f32_e32 v20, v20, v21
	v_add_f32_e32 v22, v22, v23
	v_cndmask_b32_e64 v11, v22, v20, s[2:3]
	v_pk_mul_f32 v[20:21], v[2:3], v[32:33]
	v_pk_mul_f32 v[22:23], v[2:3], v[32:33] op_sel:[1,0] op_sel_hi:[0,1]
	v_sub_f32_e32 v20, v20, v21
	v_add_f32_e32 v22, v22, v23
	v_cndmask_b32_e64 v14, v22, v20, s[2:3]
	v_pk_mul_f32 v[20:21], v[2:3], v[34:35]
	v_pk_mul_f32 v[22:23], v[2:3], v[34:35] op_sel:[1,0] op_sel_hi:[0,1]
	v_sub_f32_e32 v20, v20, v21
	v_add_f32_e32 v22, v22, v23
	v_cndmask_b32_e64 v13, v22, v20, s[2:3]
	v_pk_mul_f32 v[20:21], v[2:3], v[36:37]
	v_pk_mul_f32 v[22:23], v[2:3], v[36:37] op_sel:[1,0] op_sel_hi:[0,1]
	v_sub_f32_e32 v20, v20, v21
	v_add_f32_e32 v22, v22, v23
	v_cndmask_b32_e64 v16, v22, v20, s[2:3]
	v_pk_mul_f32 v[20:21], v[2:3], v[38:39]
	v_pk_mul_f32 v[22:23], v[2:3], v[38:39] op_sel:[1,0] op_sel_hi:[0,1]
	v_sub_f32_e32 v20, v20, v21
	v_add_f32_e32 v22, v22, v23
	v_cndmask_b32_e64 v15, v22, v20, s[2:3]
	s_branch .LBB0_1053

; #define PG8_STAGE(bufoff, gbase, voff) do { _Pragma("unroll") for (int _i = 0; _i < 2; ++_i) \
;         __builtin_amdgcn_global_load_lds((const unsigned*)((const char*)(gbase) + (voff)[_i]), (LAS unsigned*)(lds + (bufoff) + ldsw + _i * 8192), 16, 0, 0); } while (0)
; #define PG8_LDA(dst, b, h) do { _Pragma("unroll") for (int m = 0; m < 4; ++m) _Pragma("unroll") for (int k = 0; k < 2; ++k) dst[m][k] = *(const LAS bf16x8*)(lds + PG8_SA(b, h) + aoff + m * 2048 + k * 1024); } while (0)
; #define PG8_LDB(dst, b, h) do { _Pragma("unroll") for (int n = 0; n < 2; ++n) _Pragma("unroll") for (int k = 0; k < 2; ++k) dst[n][k] = *(const LAS bf16x8*)(lds + PG8_SB(b, h) + boff + n * 2048 + k * 1024); } while (0)
; #define PG8_MMA(ai, bj, At, Bt) do { __builtin_amdgcn_s_setprio(1); _Pragma("unroll") for (int m = 0; m < 4; ++m) _Pragma("unroll") for (int n = 0; n < 2; ++n) _Pragma("unroll") for (int k = 0; k < 2; ++k) \
;         acc[ai][bj][m][n] = __builtin_amdgcn_mfma_f32_16x16x32_bf16(Bt[n][k], At[m][k], acc[ai][bj][m][n], 0, 0, 0); __builtin_amdgcn_s_setprio(0); } while (0)
; #define PG8_WAIT_L(n) asm volatile("s_waitcnt lgkmcnt(" #n ")" ::: "memory")
; #define PG8_BAR __builtin_amdgcn_s_barrier()
; #define PG8_SCHED __builtin_amdgcn_sched_barrier(0)
; template <class Epi>
; DEVI void gemm_phase(LAS unsigned char* lds, const Gemm g, const Epi& E) {
;     ...
;             PG8_LDB(B0, 0, 0); PG8_SCHED; PG8_LDA(At, 0, 0); PG8_STAGE(PG8_SA(1, 1), a1 + hstepA, voffA);
;             PG8_WAIT_L(8); PG8_BAR; PG8_WAIT_L(0); PG8_MMA(0, 0, At, B0); PG8_BAR; PG8_SCHED;
;             PG8_LDB(B1, 0, 1); PG8_STAGE(PG8_SB(0, 0), b2, voffB);
;             PG8_BAR; PG8_WAIT_L(0); PG8_MMA(0, 1, At, B1); PG8_BAR;
;             PG8_LDA(At, 0, 1); PG8_STAGE(PG8_SA(0, 0), a2, voffA);
;             PG8_BAR; PG8_WAIT_L(0); PG8_MMA(1, 0, At, B0); PG8_BAR; PG8_SCHED;
.LBB0_1595:
	s_add_u32 s18, s8, 0xfffc0080
	s_addc_u32 s19, s9, -1
	s_add_i32 s26, 0, 0x10000
	v_add_u32_e32 v142, s26, v191
	ds_read_b128 v[130:133], v142
	ds_read_b128 v[134:137], v142 offset:1024
	ds_read_b128 v[138:141], v142 offset:2048
	ds_read_b128 v[142:145], v142 offset:3072
	s_cmp_eq_u32 s17, 12
	s_cselect_b32 s81, s0, s19
	s_cselect_b32 s80, s1, s18
	s_cselect_b32 s79, s37, s15
	s_cselect_b32 s78, s36, s13
	v_lshl_add_u64 v[162:163], s[8:9], 0, v[152:153]
	s_add_i32 m0, s69, 0xc000
	ds_read_b128 v[178:181], v196
	ds_read_b128 v[182:185], v196 offset:1024
	ds_read_b128 v[186:189], v196 offset:2048
	ds_read_b128 v[198:201], v196 offset:3072
	ds_read_b128 v[202:205], v196 offset:4096
	ds_read_b128 v[206:209], v196 offset:5120
	ds_read_b128 v[214:217], v196 offset:6144
	ds_read_b128 v[218:221], v196 offset:7168
	global_load_lds_dwordx4 v[162:163], off
	s_add_i32 m0, s69, 0xe000
	v_lshl_add_u64 v[162:163], s[8:9], 0, v[176:177]
	global_load_lds_dwordx4 v[162:163], off
	s_waitcnt lgkmcnt(8)
	s_barrier
	s_waitcnt lgkmcnt(0)
	v_mfma_f32_16x16x32_bf16 v[126:129], v[130:133], v[178:181], v[126:129]
	v_mfma_f32_16x16x32_bf16 v[122:125], v[138:141], v[178:181], v[122:125]
	v_mfma_f32_16x16x32_bf16 v[110:113], v[130:133], v[186:189], v[110:113]
	v_mfma_f32_16x16x32_bf16 v[106:109], v[138:141], v[186:189], v[106:109]
	v_mfma_f32_16x16x32_bf16 v[94:97], v[130:133], v[202:205], v[94:97]
	v_mfma_f32_16x16x32_bf16 v[90:93], v[138:141], v[202:205], v[90:93]
	v_mfma_f32_16x16x32_bf16 v[78:81], v[130:133], v[214:217], v[78:81]
	v_mfma_f32_16x16x32_bf16 v[74:77], v[138:141], v[214:217], v[74:77]
	v_mfma_f32_16x16x32_bf16 v[126:129], v[134:137], v[182:185], v[126:129]
	v_mfma_f32_16x16x32_bf16 v[122:125], v[142:145], v[182:185], v[122:125]
	v_mfma_f32_16x16x32_bf16 v[110:113], v[134:137], v[198:201], v[110:113]
	v_mfma_f32_16x16x32_bf16 v[106:109], v[142:145], v[198:201], v[106:109]
	v_mfma_f32_16x16x32_bf16 v[94:97], v[134:137], v[206:209], v[94:97]
	v_mfma_f32_16x16x32_bf16 v[90:93], v[142:145], v[206:209], v[90:93]
	v_mfma_f32_16x16x32_bf16 v[78:81], v[134:137], v[218:221], v[78:81]
	v_mfma_f32_16x16x32_bf16 v[74:77], v[142:145], v[218:221], v[74:77]
	s_barrier
	s_add_i32 s27, 0, 0x14000
	v_add_u32_e32 v162, s27, v191
	s_add_i32 s18, s26, s82
	ds_read_b128 v[222:225], v162
	ds_read_b128 v[226:229], v162 offset:1024
	ds_read_b128 v[230:233], v162 offset:2048
	ds_read_b128 v[234:237], v162 offset:3072
	v_lshl_add_u64 v[162:163], s[78:79], 0, v[8:9]
	s_mov_b32 m0, s18
	v_lshl_add_u64 v[164:165], s[78:79], 0, v[150:151]
	global_load_lds_dwordx4 v[162:163], off
	s_add_i32 m0, s18, 0x2000
	s_nop 0
	global_load_lds_dwordx4 v[164:165], off
	s_barrier
	s_waitcnt lgkmcnt(0)
	v_mfma_f32_16x16x32_bf16 v[118:121], v[222:225], v[178:181], v[118:121]
	v_mfma_f32_16x16x32_bf16 v[114:117], v[230:233], v[178:181], v[114:117]
	v_mfma_f32_16x16x32_bf16 v[102:105], v[222:225], v[186:189], v[102:105]
	v_mfma_f32_16x16x32_bf16 v[98:101], v[230:233], v[186:189], v[98:101]
	v_mfma_f32_16x16x32_bf16 v[86:89], v[222:225], v[202:205], v[86:89]
	v_mfma_f32_16x16x32_bf16 v[82:85], v[230:233], v[202:205], v[82:85]
	v_mfma_f32_16x16x32_bf16 v[70:73], v[222:225], v[214:217], v[70:73]
	v_mfma_f32_16x16x32_bf16 v[66:69], v[230:233], v[214:217], v[66:69]
	v_mfma_f32_16x16x32_bf16 v[118:121], v[226:229], v[182:185], v[118:121]
	v_mfma_f32_16x16x32_bf16 v[114:117], v[234:237], v[182:185], v[114:117]
	v_mfma_f32_16x16x32_bf16 v[102:105], v[226:229], v[198:201], v[102:105]
	v_mfma_f32_16x16x32_bf16 v[98:101], v[234:237], v[198:201], v[98:101]
	v_mfma_f32_16x16x32_bf16 v[86:89], v[226:229], v[206:209], v[86:89]
	v_mfma_f32_16x16x32_bf16 v[82:85], v[234:237], v[206:209], v[82:85]
	v_mfma_f32_16x16x32_bf16 v[70:73], v[226:229], v[218:221], v[70:73]
	v_mfma_f32_16x16x32_bf16 v[66:69], v[234:237], v[218:221], v[66:69]
	s_mov_b32 m0, s69
	v_lshl_add_u64 v[238:239], s[80:81], 0, v[146:147]
	s_barrier
	ds_read_b128 v[178:181], v196 offset:16384
	ds_read_b128 v[182:185], v196 offset:17408
	ds_read_b128 v[186:189], v196 offset:18432
	ds_read_b128 v[198:201], v196 offset:19456
	ds_read_b128 v[202:205], v196 offset:20480
	ds_read_b128 v[206:209], v196 offset:21504
	ds_read_b128 v[214:217], v196 offset:22528
	ds_read_b128 v[218:221], v196 offset:23552
	global_load_lds_dwordx4 v[238:239], off
	s_mov_b32 m0, s83
	v_lshl_add_u64 v[240:241], s[80:81], 0, v[148:149]
	global_load_lds_dwordx4 v[240:241], off
	s_barrier
	s_waitcnt lgkmcnt(0)
	v_mfma_f32_16x16x32_bf16 v[62:65], v[130:133], v[178:181], v[62:65]
	v_mfma_f32_16x16x32_bf16 v[58:61], v[138:141], v[178:181], v[58:61]
	v_mfma_f32_16x16x32_bf16 v[46:49], v[130:133], v[186:189], v[46:49]
	v_mfma_f32_16x16x32_bf16 v[42:45], v[138:141], v[186:189], v[42:45]
	v_mfma_f32_16x16x32_bf16 v[30:33], v[130:133], v[202:205], v[30:33]
	v_mfma_f32_16x16x32_bf16 v[26:29], v[138:141], v[202:205], v[26:29]
	v_mfma_f32_16x16x32_bf16 v[14:17], v[130:133], v[214:217], v[14:17]
	v_mfma_f32_16x16x32_bf16 v[10:13], v[138:141], v[214:217], v[10:13]
	v_mfma_f32_16x16x32_bf16 v[62:65], v[134:137], v[182:185], v[62:65]
	v_mfma_f32_16x16x32_bf16 v[58:61], v[142:145], v[182:185], v[58:61]
	v_mfma_f32_16x16x32_bf16 v[46:49], v[134:137], v[198:201], v[46:49]
	v_mfma_f32_16x16x32_bf16 v[42:45], v[142:145], v[198:201], v[42:45]
	v_mfma_f32_16x16x32_bf16 v[30:33], v[134:137], v[206:209], v[30:33]
	v_mfma_f32_16x16x32_bf16 v[26:29], v[142:145], v[206:209], v[26:29]
	v_mfma_f32_16x16x32_bf16 v[14:17], v[134:137], v[218:221], v[14:17]
	v_mfma_f32_16x16x32_bf16 v[10:13], v[142:145], v[218:221], v[10:13]
	s_barrier
; #define PG8_STAGE(bufoff, gbase, voff) do { _Pragma("unroll") for (int _i = 0; _i < 2; ++_i) \
;         __builtin_amdgcn_global_load_lds((const unsigned*)((const char*)(gbase) + (voff)[_i]), (LAS unsigned*)(lds + (bufoff) + ldsw + _i * 8192), 16, 0, 0); } while (0)
; #define PG8_LDA(dst, b, h) do { _Pragma("unroll") for (int m = 0; m < 4; ++m) _Pragma("unroll") for (int k = 0; k < 2; ++k) dst[m][k] = *(const LAS bf16x8*)(lds + PG8_SA(b, h) + aoff + m * 2048 + k * 1024); } while (0)
; #define PG8_LDB(dst, b, h) do { _Pragma("unroll") for (int n = 0; n < 2; ++n) _Pragma("unroll") for (int k = 0; k < 2; ++k) dst[n][k] = *(const LAS bf16x8*)(lds + PG8_SB(b, h) + boff + n * 2048 + k * 1024); } while (0)
; #define PG8_MMA(ai, bj, At, Bt) do { __builtin_amdgcn_s_setprio(1); _Pragma("unroll") for (int m = 0; m < 4; ++m) _Pragma("unroll") for (int n = 0; n < 2; ++n) _Pragma("unroll") for (int k = 0; k < 2; ++k) \
;         acc[ai][bj][m][n] = __builtin_amdgcn_mfma_f32_16x16x32_bf16(Bt[n][k], At[m][k], acc[ai][bj][m][n], 0, 0, 0); __builtin_amdgcn_s_setprio(0); } while (0)
; #define PG8_WAIT_V(n) asm volatile("s_waitcnt vmcnt(" #n ")" ::: "memory")
; #define PG8_WAIT_L(n) asm volatile("s_waitcnt lgkmcnt(" #n ")" ::: "memory")
; #define PG8_BAR __builtin_amdgcn_s_barrier()
; #define PG8_SCHED __builtin_amdgcn_sched_barrier(0)
; template <class Epi>
; DEVI void gemm_phase(LAS unsigned char* lds, const Gemm g, const Epi& E) {
;     ...
;             PG8_STAGE(PG8_SB(0, 1), b2 + hstepB, voffB);
;             PG8_WAIT_V(6); PG8_BAR; PG8_MMA(1, 1, At, B1); PG8_BAR;
;             PG8_LDB(B0, 1, 0); PG8_SCHED; PG8_LDA(At, 1, 0); PG8_STAGE(PG8_SA(0, 1), a2 + hstepA, voffA);
;             PG8_WAIT_L(8); PG8_BAR; PG8_WAIT_L(0); PG8_MMA(0, 0, At, B0); PG8_BAR; PG8_SCHED;
;             PG8_LDB(B1, 1, 1); PG8_STAGE(PG8_SB(1, 0), b3, voffB);
;             PG8_BAR; PG8_WAIT_L(0); PG8_MMA(0, 1, At, B1); PG8_BAR;
;             PG8_LDA(At, 1, 1); PG8_STAGE(PG8_SA(1, 0), a3, voffA);
	s_add_u32 s18, s78, 0x40000
	s_addc_u32 s19, s79, 0
	s_add_i32 s26, s27, s82
	s_mov_b32 m0, s26
	v_lshl_add_u64 v[130:131], s[18:19], 0, v[8:9]
	global_load_lds_dwordx4 v[130:131], off
	s_add_i32 m0, s26, 0x2000
	v_lshl_add_u64 v[130:131], s[18:19], 0, v[150:151]
	global_load_lds_dwordx4 v[130:131], off
	s_waitcnt vmcnt(6)
	s_barrier
	v_mfma_f32_16x16x32_bf16 v[54:57], v[222:225], v[178:181], v[54:57]
	v_mfma_f32_16x16x32_bf16 v[50:53], v[230:233], v[178:181], v[50:53]
	v_mfma_f32_16x16x32_bf16 v[38:41], v[222:225], v[186:189], v[38:41]
	v_mfma_f32_16x16x32_bf16 v[34:37], v[230:233], v[186:189], v[34:37]
	v_mfma_f32_16x16x32_bf16 v[22:25], v[222:225], v[202:205], v[22:25]
	v_mfma_f32_16x16x32_bf16 v[18:21], v[230:233], v[202:205], v[18:21]
	v_mfma_f32_16x16x32_bf16 v[4:7], v[222:225], v[214:217], v[4:7]
	v_mfma_f32_16x16x32_bf16 v[0:3], v[230:233], v[214:217], v[0:3]
	v_mfma_f32_16x16x32_bf16 v[54:57], v[226:229], v[182:185], v[54:57]
	v_mfma_f32_16x16x32_bf16 v[50:53], v[234:237], v[182:185], v[50:53]
	v_mfma_f32_16x16x32_bf16 v[38:41], v[226:229], v[198:201], v[38:41]
	v_mfma_f32_16x16x32_bf16 v[34:37], v[234:237], v[198:201], v[34:37]
	v_mfma_f32_16x16x32_bf16 v[22:25], v[226:229], v[206:209], v[22:25]
	v_mfma_f32_16x16x32_bf16 v[18:21], v[234:237], v[206:209], v[18:21]
	v_mfma_f32_16x16x32_bf16 v[4:7], v[226:229], v[218:221], v[4:7]
	v_mfma_f32_16x16x32_bf16 v[0:3], v[234:237], v[218:221], v[0:3]
	s_add_i32 s26, 0, 0x18000
	v_add_u32_e32 v142, s26, v191
	s_barrier
	ds_read_b128 v[130:133], v142
	ds_read_b128 v[134:137], v142 offset:1024
	ds_read_b128 v[138:141], v142 offset:2048
	ds_read_b128 v[142:145], v142 offset:3072
	s_add_u32 s18, s80, 0x40000
	s_addc_u32 s19, s81, 0
	s_mov_b32 m0, s84
	v_lshl_add_u64 v[222:223], s[18:19], 0, v[146:147]
	ds_read_b128 v[178:181], v196 offset:32768
	ds_read_b128 v[182:185], v196 offset:33792
	ds_read_b128 v[186:189], v196 offset:34816
	ds_read_b128 v[198:201], v196 offset:35840
	ds_read_b128 v[202:205], v196 offset:36864
	ds_read_b128 v[206:209], v196 offset:37888
	ds_read_b128 v[214:217], v196 offset:38912
	ds_read_b128 v[218:221], v196 offset:39936
	global_load_lds_dwordx4 v[222:223], off
	s_mov_b32 m0, s85
	v_lshl_add_u64 v[222:223], s[18:19], 0, v[148:149]
	global_load_lds_dwordx4 v[222:223], off
	s_waitcnt lgkmcnt(8)
	s_barrier
	s_waitcnt lgkmcnt(0)
	v_mfma_f32_16x16x32_bf16 v[126:129], v[130:133], v[178:181], v[126:129]
	v_mfma_f32_16x16x32_bf16 v[122:125], v[138:141], v[178:181], v[122:125]
	v_mfma_f32_16x16x32_bf16 v[110:113], v[130:133], v[186:189], v[110:113]
	v_mfma_f32_16x16x32_bf16 v[106:109], v[138:141], v[186:189], v[106:109]
	v_mfma_f32_16x16x32_bf16 v[94:97], v[130:133], v[202:205], v[94:97]
	v_mfma_f32_16x16x32_bf16 v[90:93], v[138:141], v[202:205], v[90:93]
	v_mfma_f32_16x16x32_bf16 v[78:81], v[130:133], v[214:217], v[78:81]
	v_mfma_f32_16x16x32_bf16 v[74:77], v[138:141], v[214:217], v[74:77]
	v_mfma_f32_16x16x32_bf16 v[126:129], v[134:137], v[182:185], v[126:129]
	v_mfma_f32_16x16x32_bf16 v[122:125], v[142:145], v[182:185], v[122:125]
	v_mfma_f32_16x16x32_bf16 v[110:113], v[134:137], v[198:201], v[110:113]
	v_mfma_f32_16x16x32_bf16 v[106:109], v[142:145], v[198:201], v[106:109]
	v_mfma_f32_16x16x32_bf16 v[94:97], v[134:137], v[206:209], v[94:97]
	v_mfma_f32_16x16x32_bf16 v[90:93], v[142:145], v[206:209], v[90:93]
	v_mfma_f32_16x16x32_bf16 v[78:81], v[134:137], v[218:221], v[78:81]
	v_mfma_f32_16x16x32_bf16 v[74:77], v[142:145], v[218:221], v[74:77]
	s_barrier
	s_add_i32 s27, 0, 0x1c000
	s_add_i32 s18, s26, s82
	v_add_u32_e32 v197, s27, v191
	v_lshl_add_u64 v[162:163], v[162:163], 0, s[70:71]
	s_mov_b32 m0, s18
	ds_read_b128 v[222:225], v197
	ds_read_b128 v[226:229], v197 offset:1024
	ds_read_b128 v[230:233], v197 offset:2048
	ds_read_b128 v[234:237], v197 offset:3072
	global_load_lds_dwordx4 v[162:163], off
	s_add_i32 m0, s18, 0x2000
	v_lshl_add_u64 v[162:163], v[164:165], 0, s[70:71]
	global_load_lds_dwordx4 v[162:163], off
	s_barrier
	s_waitcnt lgkmcnt(0)
	v_mfma_f32_16x16x32_bf16 v[118:121], v[222:225], v[178:181], v[118:121]
	v_mfma_f32_16x16x32_bf16 v[114:117], v[230:233], v[178:181], v[114:117]
	v_mfma_f32_16x16x32_bf16 v[102:105], v[222:225], v[186:189], v[102:105]
	v_mfma_f32_16x16x32_bf16 v[98:101], v[230:233], v[186:189], v[98:101]
	v_mfma_f32_16x16x32_bf16 v[86:89], v[222:225], v[202:205], v[86:89]
	v_mfma_f32_16x16x32_bf16 v[82:85], v[230:233], v[202:205], v[82:85]
	v_mfma_f32_16x16x32_bf16 v[70:73], v[222:225], v[214:217], v[70:73]
	v_mfma_f32_16x16x32_bf16 v[66:69], v[230:233], v[214:217], v[66:69]
	v_mfma_f32_16x16x32_bf16 v[118:121], v[226:229], v[182:185], v[118:121]
	v_mfma_f32_16x16x32_bf16 v[114:117], v[234:237], v[182:185], v[114:117]
	v_mfma_f32_16x16x32_bf16 v[102:105], v[226:229], v[198:201], v[102:105]
	v_mfma_f32_16x16x32_bf16 v[98:101], v[234:237], v[198:201], v[98:101]
	v_mfma_f32_16x16x32_bf16 v[86:89], v[226:229], v[206:209], v[86:89]
	v_mfma_f32_16x16x32_bf16 v[82:85], v[234:237], v[206:209], v[82:85]
	v_mfma_f32_16x16x32_bf16 v[70:73], v[226:229], v[218:221], v[70:73]
	v_mfma_f32_16x16x32_bf16 v[66:69], v[234:237], v[218:221], v[66:69]
	s_mov_b32 m0, s86
	v_lshl_add_u64 v[162:163], v[238:239], 0, s[70:71]
	s_barrier
	ds_read_b128 v[178:181], v196 offset:49152
	ds_read_b128 v[182:185], v196 offset:50176
	ds_read_b128 v[186:189], v196 offset:51200
	ds_read_b128 v[198:201], v196 offset:52224
	ds_read_b128 v[202:205], v196 offset:53248
	ds_read_b128 v[206:209], v196 offset:54272
	ds_read_b128 v[214:217], v196 offset:55296
	ds_read_b128 v[218:221], v196 offset:56320
	global_load_lds_dwordx4 v[162:163], off
	s_mov_b32 m0, s87
	v_lshl_add_u64 v[162:163], v[240:241], 0, s[70:71]
	global_load_lds_dwordx4 v[162:163], off
	s_barrier
; #define LAS __attribute__((address_space(3)))
; #define PG8_STAGE(bufoff, gbase, voff) do { _Pragma("unroll") for (int _i = 0; _i < 2; ++_i) \
;         __builtin_amdgcn_global_load_lds((const unsigned*)((const char*)(gbase) + (voff)[_i]), (LAS unsigned*)(lds + (bufoff) + ldsw + _i * 8192), 16, 0, 0); } while (0)
; #define PG8_WAIT_V(n) asm volatile("s_waitcnt vmcnt(" #n ")" ::: "memory")
; template <class Epi>
; DEVI void gemm_phase(LAS unsigned char* lds, const Gemm g, const Epi& E) {
;     ...
;             PG8_BAR; PG8_WAIT_L(0); PG8_MMA(1, 0, At, B0); PG8_BAR; PG8_SCHED;
;             PG8_STAGE(PG8_SB(1, 1), b3 + hstepB, voffB);
;             PG8_WAIT_V(6); PG8_BAR; PG8_MMA(1, 1, At, B1); PG8_BAR;
;     ...
;                 if constexpr (Epi::PRE) {
; #pragma unroll
;                     for (int m = 0; m < 2; ++m)
; #pragma unroll
;                         for (int bj = 0; bj < 2; ++bj)
; #pragma unroll
;                             for (int n = 0; n < 2; ++n) pre[m][bj][n] = E.load(row0 + ai * HALF + (m0 + m) * 16, col0 + bj * HALF + n * NST);
;                 }
; #pragma unroll
;                 for (int mm = 0; mm < 2; ++mm) {
;                     const int m = m0 + mm;
;                     const int r = row0 + ai * HALF + m * 16; float rs = 1.f, part = 0.f;
;                     if constexpr (Epi::RS) rs = rsv[ai * 4 + m];
;                     if constexpr (Epi::PAIR) E.pair8(cur.b, r, cur.pn * HALF + wc * 32 + 8 * fq, acc[ai][0][m][0] * rs, acc[ai][0][m][1] * rs, acc[ai][1][m][0] * rs, acc[ai][1][m][1] * rs);
;                     else
; #pragma unroll
;                     for (int bj = 0; bj < 2; ++bj) {
;                         const int c = col0 + bj * HALF; f32x4 v0 = acc[ai][bj][m][0], v1 = acc[ai][bj][m][1];
;                         if constexpr (Epi::RS) { v0 = v0 * rs; v1 = v1 * rs; }
;                         if constexpr (Epi::PRE) part += E.frag_pre8(cur.b, r, c, v0, v1, pre[mm][bj][0], pre[mm][bj][1]);
;                         else if constexpr (Epi::PERM) E.frag8(cur.b, r, c, v0, v1);
;                         else { E.frag(cur.b, r, c, v0); E.frag(cur.b, r, c + 16, v1); }
;                     }
;                     if constexpr (Epi::SSQ) { part += __shfl_xor(part, 16); part += __shfl_xor(part, 32); if (fq == 0) ((LAS float*)(lds + 131072))[(wr * 4 + wc) * 128 + ai * 64 + m * 16 + fr] = part; }
	s_waitcnt lgkmcnt(0)
	v_mfma_f32_16x16x32_bf16 v[62:65], v[130:133], v[178:181], v[62:65]
	v_mfma_f32_16x16x32_bf16 v[58:61], v[138:141], v[178:181], v[58:61]
	v_mfma_f32_16x16x32_bf16 v[46:49], v[130:133], v[186:189], v[46:49]
	v_mfma_f32_16x16x32_bf16 v[42:45], v[138:141], v[186:189], v[42:45]
	v_mfma_f32_16x16x32_bf16 v[30:33], v[130:133], v[202:205], v[30:33]
	v_mfma_f32_16x16x32_bf16 v[26:29], v[138:141], v[202:205], v[26:29]
	v_mfma_f32_16x16x32_bf16 v[14:17], v[130:133], v[214:217], v[14:17]
	v_mfma_f32_16x16x32_bf16 v[10:13], v[138:141], v[214:217], v[10:13]
	v_mfma_f32_16x16x32_bf16 v[62:65], v[134:137], v[182:185], v[62:65]
	v_mfma_f32_16x16x32_bf16 v[58:61], v[142:145], v[182:185], v[58:61]
	v_mfma_f32_16x16x32_bf16 v[46:49], v[134:137], v[198:201], v[46:49]
	v_mfma_f32_16x16x32_bf16 v[42:45], v[142:145], v[198:201], v[42:45]
	v_mfma_f32_16x16x32_bf16 v[30:33], v[134:137], v[206:209], v[30:33]
	v_mfma_f32_16x16x32_bf16 v[26:29], v[142:145], v[206:209], v[26:29]
	v_mfma_f32_16x16x32_bf16 v[14:17], v[134:137], v[218:221], v[14:17]
	v_mfma_f32_16x16x32_bf16 v[10:13], v[142:145], v[218:221], v[10:13]
	s_barrier
	s_add_u32 s18, s78, 0x40080
	s_addc_u32 s19, s79, 0
	s_add_i32 s26, s27, s82
	s_mov_b32 m0, s26
	v_lshl_add_u64 v[130:131], s[18:19], 0, v[8:9]
	global_load_lds_dwordx4 v[130:131], off
	s_add_i32 m0, s26, 0x2000
	v_lshl_add_u64 v[130:131], s[18:19], 0, v[150:151]
	global_load_lds_dwordx4 v[130:131], off
	s_waitcnt vmcnt(6)
	s_barrier
	v_mfma_f32_16x16x32_bf16 v[54:57], v[222:225], v[178:181], v[54:57]
	v_mfma_f32_16x16x32_bf16 v[50:53], v[230:233], v[178:181], v[50:53]
	v_mfma_f32_16x16x32_bf16 v[38:41], v[222:225], v[186:189], v[38:41]
	v_mfma_f32_16x16x32_bf16 v[34:37], v[230:233], v[186:189], v[34:37]
	v_mfma_f32_16x16x32_bf16 v[22:25], v[222:225], v[202:205], v[22:25]
	v_mfma_f32_16x16x32_bf16 v[18:21], v[230:233], v[202:205], v[18:21]
	v_mfma_f32_16x16x32_bf16 v[4:7], v[222:225], v[214:217], v[4:7]
	v_mfma_f32_16x16x32_bf16 v[0:3], v[230:233], v[214:217], v[0:3]
	v_mfma_f32_16x16x32_bf16 v[54:57], v[226:229], v[182:185], v[54:57]
	v_mfma_f32_16x16x32_bf16 v[50:53], v[234:237], v[182:185], v[50:53]
	v_mfma_f32_16x16x32_bf16 v[38:41], v[226:229], v[198:201], v[38:41]
	v_mfma_f32_16x16x32_bf16 v[34:37], v[234:237], v[198:201], v[34:37]
	v_mfma_f32_16x16x32_bf16 v[22:25], v[226:229], v[206:209], v[22:25]
	v_mfma_f32_16x16x32_bf16 v[18:21], v[234:237], v[206:209], v[18:21]
	v_mfma_f32_16x16x32_bf16 v[4:7], v[226:229], v[218:221], v[4:7]
	v_mfma_f32_16x16x32_bf16 v[0:3], v[234:237], v[218:221], v[0:3]
	s_add_i32 s17, s17, 2
	s_add_u32 s8, s8, 0x100
	s_addc_u32 s9, s9, 0
	s_add_u32 s13, s13, 0x100
	s_addc_u32 s15, s15, 0
	s_cmp_gt_u32 s17, 13
	s_barrier
	s_cbranch_scc0 .LBB0_1595
	s_setprio 0
	s_lshl_b32 s0, s68, 8
	v_add_u32_e32 v182, s0, v190
	v_lshl_or_b32 v180, s12, 8, v195
	v_ashrrev_i32_e32 v183, 31, v182
	v_lshlrev_b64 v[130:131], 12, v[182:183]
	v_ashrrev_i32_e32 v181, 31, v180
	v_lshl_add_u64 v[130:131], s[30:31], 0, v[130:131]
	v_lshlrev_b64 v[184:185], 2, v[180:181]
	v_lshl_add_u64 v[162:163], v[130:131], 0, v[184:185]
	global_load_dwordx4 v[200:203], v[162:163], off nt
	global_load_dwordx4 v[204:207], v[162:163], off offset:16 nt
	global_load_dwordx4 v[214:217], v[162:163], off offset:512 nt
	global_load_dwordx4 v[218:221], v[162:163], off offset:528 nt
	v_or_b32_e32 v188, 16, v182
	v_ashrrev_i32_e32 v189, 31, v188
	v_lshlrev_b64 v[130:131], 12, v[188:189]
	v_lshl_add_u64 v[130:131], s[30:31], 0, v[130:131]
	v_lshl_add_u64 v[186:187], v[130:131], 0, v[184:185]
	global_load_dwordx4 v[138:141], v[186:187], off offset:16
	global_load_dwordx4 v[142:145], v[186:187], off
	global_load_dwordx4 v[130:133], v[186:187], off offset:528
	global_load_dwordx4 v[134:137], v[186:187], off offset:512
	v_and_b32_e32 v165, 64, v155
	v_xor_b32_e32 v164, 16, v155
	v_add_u32_e32 v165, 64, v165
	v_xor_b32_e32 v179, 32, v155
	v_cmp_lt_i32_e32 vcc, v164, v165
	v_or_b32_e32 v178, 0x80, v180
	s_waitcnt vmcnt(0)
	v_pk_add_f32 v[128:129], v[128:129], v[202:203]
	v_cndmask_b32_e32 v164, v155, v164, vcc
	v_cmp_lt_i32_e32 vcc, v179, v165
	v_lshlrev_b32_e32 v198, 2, v164
	v_pk_add_f32 v[126:127], v[126:127], v[200:201]
	v_cndmask_b32_e32 v165, v155, v179, vcc
	v_lshlrev_b32_e32 v197, 2, v165
	v_lshlrev_b64 v[164:165], 10, v[182:183]
	v_pk_add_f32 v[124:125], v[124:125], v[206:207]
	v_pk_add_f32 v[122:123], v[122:123], v[204:205]
	v_pk_add_f32 v[120:121], v[120:121], v[216:217]
	v_pk_add_f32 v[118:119], v[118:119], v[214:215]
	v_pk_add_f32 v[202:203], v[116:117], v[220:221]
	v_pk_add_f32 v[200:201], v[114:115], v[218:219]
	v_lshl_add_u64 v[208:209], v[164:165], 0, v[180:181]
	global_store_dwordx4 v[162:163], v[126:129], off nt
	global_store_dwordx4 v[162:163], v[122:125], off offset:16 nt
	v_cvt_pk_bf16_f32 v114, v126, v127
	v_cvt_pk_bf16_f32 v115, v128, v129
	v_cvt_pk_bf16_f32 v116, v122, v123
	v_cvt_pk_bf16_f32 v117, v124, v125
	v_mul_f32_e32 v127, v127, v127
	v_mul_f32_e32 v129, v129, v129
	v_mul_f32_e32 v123, v123, v123
	v_mul_f32_e32 v125, v125, v125
	v_mul_f32_e32 v183, v119, v119
	v_mul_f32_e32 v199, v121, v121
	v_mul_f32_e32 v204, v201, v201
	v_mul_f32_e32 v205, v203, v203
	v_lshl_add_u64 v[208:209], v[208:209], 1, s[24:25]
	v_fmac_f32_e32 v127, v126, v126
	v_fmac_f32_e32 v129, v128, v128
	v_fmac_f32_e32 v123, v122, v122
	v_fmac_f32_e32 v125, v124, v124
	v_fmac_f32_e32 v183, v118, v118
	v_fmac_f32_e32 v199, v120, v120
	v_fmac_f32_e32 v204, v200, v200
	v_fmac_f32_e32 v205, v202, v202
	global_store_dwordx4 v[208:209], v[114:117], off
	v_ashrrev_i32_e32 v179, 31, v178
	v_lshl_add_u64 v[164:165], v[164:165], 0, v[178:179]
	v_add_f32_e32 v114, v127, v129
	v_add_f32_e32 v115, v123, v125
	v_add_f32_e32 v116, v183, v199
	v_add_f32_e32 v117, v204, v205
	v_add_f32_e32 v114, v114, v115
	v_add_f32_e32 v115, v116, v117
	v_add_f32_e32 v114, v114, v115
	ds_bpermute_b32 v115, v198, v114
	global_store_dwordx4 v[162:163], v[118:121], off offset:512 nt
	global_store_dwordx4 v[162:163], v[200:203], off offset:528 nt
	v_cvt_pk_bf16_f32 v116, v118, v119
	v_cvt_pk_bf16_f32 v117, v120, v121
	v_cvt_pk_bf16_f32 v118, v200, v201
	s_waitcnt lgkmcnt(0)
	v_add_f32_e32 v114, v114, v115
	ds_bpermute_b32 v115, v197, v114
	v_cvt_pk_bf16_f32 v119, v202, v203
	v_lshl_add_u64 v[120:121], v[164:165], 1, s[24:25]
	global_store_dwordx4 v[120:121], v[116:119], off
	s_and_saveexec_b64 s[8:9], s[2:3]
	s_cbranch_execz .LBB0_1598
	s_waitcnt lgkmcnt(0)
	v_add_f32_e32 v114, v114, v115
	ds_write_b32 v192, v114

; #define LAS __attribute__((address_space(3)))
;     DEVI f32x4 load(int r, int c) const { const bf16x4 y = *(const bf16x4*)(Y + (size_t)r * DM + c); return (f32x4){bf2f((u16)y[0]), bf2f((u16)y[1]), bf2f((u16)y[2]), bf2f((u16)y[3])}; }
; template <class Epi>
; DEVI void gemm_phase(LAS unsigned char* lds, const Gemm g, const Epi& E) {
;     ...
;                             for (int n = 0; n < 2; ++n) pre[m][bj][n] = E.load(row0 + ai * HALF + (m0 + m) * 16, col0 + bj * HALF + n * NST);
;                 }
; #pragma unroll
;                 for (int mm = 0; mm < 2; ++mm) {
;                     const int m = m0 + mm;
;                     const int r = row0 + ai * HALF + m * 16; float rs = 1.f, part = 0.f;
;                     if constexpr (Epi::RS) rs = rsv[ai * 4 + m];
;                     if constexpr (Epi::PAIR) E.pair8(cur.b, r, cur.pn * HALF + wc * 32 + 8 * fq, acc[ai][0][m][0] * rs, acc[ai][0][m][1] * rs, acc[ai][1][m][0] * rs, acc[ai][1][m][1] * rs);
;                     else
; #pragma unroll
;                     for (int bj = 0; bj < 2; ++bj) {
;                         const int c = col0 + bj * HALF; f32x4 v0 = acc[ai][bj][m][0], v1 = acc[ai][bj][m][1];
;                         if constexpr (Epi::RS) { v0 = v0 * rs; v1 = v1 * rs; }
;                         if constexpr (Epi::PRE) part += E.frag_pre8(cur.b, r, c, v0, v1, pre[mm][bj][0], pre[mm][bj][1]);
;                         else if constexpr (Epi::PERM) E.frag8(cur.b, r, c, v0, v1);
;                         else { E.frag(cur.b, r, c, v0); E.frag(cur.b, r, c + 16, v1); }
;                     }
;                     if constexpr (Epi::SSQ) { part += __shfl_xor(part, 16); part += __shfl_xor(part, 32); if (fq == 0) ((LAS float*)(lds + 131072))[(wr * 4 + wc) * 128 + ai * 64 + m * 16 + fr] = part; }
.LBB0_1600:
	s_or_b64 exec, exec, s[8:9]
	v_or_b32_e32 v134, 32, v182
	v_ashrrev_i32_e32 v135, 31, v134
	s_waitcnt lgkmcnt(0)
	v_lshlrev_b64 v[98:99], 12, v[134:135]
	v_lshl_add_u64 v[98:99], s[30:31], 0, v[98:99]
	v_lshl_add_u64 v[136:137], v[98:99], 0, v[184:185]
	global_load_dwordx4 v[118:121], v[136:137], off nt
	global_load_dwordx4 v[122:125], v[136:137], off offset:16 nt
	global_load_dwordx4 v[126:129], v[136:137], off offset:512 nt
	global_load_dwordx4 v[130:133], v[136:137], off offset:528 nt
	v_or_b32_e32 v116, 48, v182
	v_ashrrev_i32_e32 v117, 31, v116
	v_lshlrev_b64 v[98:99], 12, v[116:117]
	v_lshl_add_u64 v[98:99], s[30:31], 0, v[98:99]
	v_lshl_add_u64 v[114:115], v[98:99], 0, v[184:185]
	global_load_dwordx4 v[106:109], v[114:115], off offset:16
	global_load_dwordx4 v[110:113], v[114:115], off
	global_load_dwordx4 v[98:101], v[114:115], off offset:528
	global_load_dwordx4 v[102:105], v[114:115], off offset:512
	v_lshlrev_b64 v[134:135], 10, v[134:135]
	v_lshl_add_u64 v[138:139], v[134:135], 0, v[180:181]
	v_lshl_add_u64 v[138:139], v[138:139], 1, s[24:25]
	v_lshl_add_u64 v[134:135], v[134:135], 0, v[178:179]
	s_waitcnt vmcnt(7)
	v_pk_add_f32 v[96:97], v[96:97], v[120:121]
	v_pk_add_f32 v[94:95], v[94:95], v[118:119]
	s_waitcnt vmcnt(6)
	v_pk_add_f32 v[92:93], v[92:93], v[124:125]
	v_pk_add_f32 v[90:91], v[90:91], v[122:123]
	s_waitcnt vmcnt(5)
	v_pk_add_f32 v[88:89], v[88:89], v[128:129]
	v_pk_add_f32 v[86:87], v[86:87], v[126:127]
	s_waitcnt vmcnt(4)
	v_pk_add_f32 v[120:121], v[84:85], v[132:133]
	v_pk_add_f32 v[118:119], v[82:83], v[130:131]
	global_store_dwordx4 v[136:137], v[94:97], off nt
	global_store_dwordx4 v[136:137], v[90:93], off offset:16 nt
	v_cvt_pk_bf16_f32 v82, v94, v95
	v_cvt_pk_bf16_f32 v83, v96, v97
	v_cvt_pk_bf16_f32 v84, v90, v91
	v_cvt_pk_bf16_f32 v85, v92, v93
	v_mul_f32_e32 v95, v95, v95
	v_mul_f32_e32 v97, v97, v97
	v_mul_f32_e32 v91, v91, v91
	v_mul_f32_e32 v93, v93, v93
	v_mul_f32_e32 v122, v87, v87
	v_mul_f32_e32 v123, v89, v89
	v_mul_f32_e32 v124, v119, v119
	v_mul_f32_e32 v125, v121, v121
	v_fmac_f32_e32 v95, v94, v94
	v_fmac_f32_e32 v97, v96, v96
	v_fmac_f32_e32 v91, v90, v90
	v_fmac_f32_e32 v93, v92, v92
	v_fmac_f32_e32 v122, v86, v86
	v_fmac_f32_e32 v123, v88, v88
	v_fmac_f32_e32 v124, v118, v118
	v_fmac_f32_e32 v125, v120, v120
	global_store_dwordx4 v[138:139], v[82:85], off
	global_store_dwordx4 v[136:137], v[86:89], off offset:512 nt
	global_store_dwordx4 v[136:137], v[118:121], off offset:528 nt
	v_add_f32_e32 v82, v95, v97
	v_add_f32_e32 v83, v91, v93
	v_add_f32_e32 v84, v122, v123
	v_add_f32_e32 v85, v124, v125
	v_add_f32_e32 v82, v82, v83
	v_add_f32_e32 v83, v84, v85
	v_add_f32_e32 v82, v82, v83
	ds_bpermute_b32 v83, v198, v82
	v_cvt_pk_bf16_f32 v84, v86, v87
	v_cvt_pk_bf16_f32 v85, v88, v89
	v_cvt_pk_bf16_f32 v86, v118, v119
	v_cvt_pk_bf16_f32 v87, v120, v121
	s_waitcnt lgkmcnt(0)
	v_add_f32_e32 v82, v82, v83
	ds_bpermute_b32 v83, v197, v82
	v_lshl_add_u64 v[88:89], v[134:135], 1, s[24:25]
	global_store_dwordx4 v[88:89], v[84:87], off
	s_and_saveexec_b64 s[8:9], s[2:3]
	s_cbranch_execz .LBB0_1602
	s_waitcnt lgkmcnt(0)
	v_add_f32_e32 v82, v82, v83
	ds_write_b32 v192, v82 offset:128

; #define LAS __attribute__((address_space(3)))
;     DEVI f32x4 load(int r, int c) const { const bf16x4 y = *(const bf16x4*)(Y + (size_t)r * DM + c); return (f32x4){bf2f((u16)y[0]), bf2f((u16)y[1]), bf2f((u16)y[2]), bf2f((u16)y[3])}; }
; template <class Epi>
; DEVI void gemm_phase(LAS unsigned char* lds, const Gemm g, const Epi& E) {
;     ...
;                             for (int n = 0; n < 2; ++n) pre[m][bj][n] = E.load(row0 + ai * HALF + (m0 + m) * 16, col0 + bj * HALF + n * NST);
;                 }
; #pragma unroll
;                 for (int mm = 0; mm < 2; ++mm) {
;                     const int m = m0 + mm;
;                     const int r = row0 + ai * HALF + m * 16; float rs = 1.f, part = 0.f;
;                     if constexpr (Epi::RS) rs = rsv[ai * 4 + m];
;                     if constexpr (Epi::PAIR) E.pair8(cur.b, r, cur.pn * HALF + wc * 32 + 8 * fq, acc[ai][0][m][0] * rs, acc[ai][0][m][1] * rs, acc[ai][1][m][0] * rs, acc[ai][1][m][1] * rs);
;                     else
; #pragma unroll
;                     for (int bj = 0; bj < 2; ++bj) {
;                         const int c = col0 + bj * HALF; f32x4 v0 = acc[ai][bj][m][0], v1 = acc[ai][bj][m][1];
;                         if constexpr (Epi::RS) { v0 = v0 * rs; v1 = v1 * rs; }
;                         if constexpr (Epi::PRE) part += E.frag_pre8(cur.b, r, c, v0, v1, pre[mm][bj][0], pre[mm][bj][1]);
;                         else if constexpr (Epi::PERM) E.frag8(cur.b, r, c, v0, v1);
;                         else { E.frag(cur.b, r, c, v0); E.frag(cur.b, r, c + 16, v1); }
;                     }
;                     if constexpr (Epi::SSQ) { part += __shfl_xor(part, 16); part += __shfl_xor(part, 32); if (fq == 0) ((LAS float*)(lds + 131072))[(wr * 4 + wc) * 128 + ai * 64 + m * 16 + fr] = part; }
.LBB0_1604:
	s_or_b64 exec, exec, s[8:9]
	v_add_u32_e32 v102, 0x80, v182
	v_ashrrev_i32_e32 v103, 31, v102
	s_waitcnt lgkmcnt(0)
	v_lshlrev_b64 v[66:67], 12, v[102:103]
	v_lshl_add_u64 v[66:67], s[30:31], 0, v[66:67]
	v_lshl_add_u64 v[104:105], v[66:67], 0, v[184:185]
	global_load_dwordx4 v[86:89], v[104:105], off nt
	global_load_dwordx4 v[90:93], v[104:105], off offset:16 nt
	global_load_dwordx4 v[94:97], v[104:105], off offset:512 nt
	global_load_dwordx4 v[98:101], v[104:105], off offset:528 nt
	v_add_u32_e32 v84, 0x90, v182
	v_ashrrev_i32_e32 v85, 31, v84
	v_lshlrev_b64 v[66:67], 12, v[84:85]
	v_lshl_add_u64 v[66:67], s[30:31], 0, v[66:67]
	v_lshl_add_u64 v[82:83], v[66:67], 0, v[184:185]
	global_load_dwordx4 v[74:77], v[82:83], off offset:16
	global_load_dwordx4 v[78:81], v[82:83], off
	global_load_dwordx4 v[66:69], v[82:83], off offset:528
	global_load_dwordx4 v[70:73], v[82:83], off offset:512
	v_lshlrev_b64 v[102:103], 10, v[102:103]
	v_lshl_add_u64 v[106:107], v[102:103], 0, v[180:181]
	v_lshl_add_u64 v[106:107], v[106:107], 1, s[24:25]
	v_lshl_add_u64 v[102:103], v[102:103], 0, v[178:179]
	s_waitcnt vmcnt(7)
	v_pk_add_f32 v[64:65], v[64:65], v[88:89]
	v_pk_add_f32 v[62:63], v[62:63], v[86:87]
	s_waitcnt vmcnt(6)
	v_pk_add_f32 v[60:61], v[60:61], v[92:93]
	v_pk_add_f32 v[58:59], v[58:59], v[90:91]
	s_waitcnt vmcnt(5)
	v_pk_add_f32 v[56:57], v[56:57], v[96:97]
	v_pk_add_f32 v[54:55], v[54:55], v[94:95]
	s_waitcnt vmcnt(4)
	v_pk_add_f32 v[88:89], v[52:53], v[100:101]
	v_pk_add_f32 v[86:87], v[50:51], v[98:99]
	global_store_dwordx4 v[104:105], v[62:65], off nt
	global_store_dwordx4 v[104:105], v[58:61], off offset:16 nt
	v_cvt_pk_bf16_f32 v50, v62, v63
	v_cvt_pk_bf16_f32 v51, v64, v65
	v_cvt_pk_bf16_f32 v52, v58, v59
	v_cvt_pk_bf16_f32 v53, v60, v61
	v_mul_f32_e32 v63, v63, v63
	v_mul_f32_e32 v65, v65, v65
	v_mul_f32_e32 v59, v59, v59
	v_mul_f32_e32 v61, v61, v61
	v_mul_f32_e32 v90, v55, v55
	v_mul_f32_e32 v91, v57, v57
	v_mul_f32_e32 v92, v87, v87
	v_mul_f32_e32 v93, v89, v89
	v_fmac_f32_e32 v63, v62, v62
	v_fmac_f32_e32 v65, v64, v64
	v_fmac_f32_e32 v59, v58, v58
	v_fmac_f32_e32 v61, v60, v60
	v_fmac_f32_e32 v90, v54, v54
	v_fmac_f32_e32 v91, v56, v56
	v_fmac_f32_e32 v92, v86, v86
	v_fmac_f32_e32 v93, v88, v88
	global_store_dwordx4 v[106:107], v[50:53], off
	global_store_dwordx4 v[104:105], v[54:57], off offset:512 nt
	global_store_dwordx4 v[104:105], v[86:89], off offset:528 nt
	v_add_f32_e32 v50, v63, v65
	v_add_f32_e32 v51, v59, v61
	v_add_f32_e32 v52, v90, v91
	v_add_f32_e32 v53, v92, v93
	v_add_f32_e32 v50, v50, v51
	v_add_f32_e32 v51, v52, v53
	v_add_f32_e32 v50, v50, v51
	ds_bpermute_b32 v51, v198, v50
	v_cvt_pk_bf16_f32 v52, v54, v55
	v_cvt_pk_bf16_f32 v53, v56, v57
	v_cvt_pk_bf16_f32 v54, v86, v87
	v_cvt_pk_bf16_f32 v55, v88, v89
	s_waitcnt lgkmcnt(0)
	v_add_f32_e32 v50, v50, v51
	ds_bpermute_b32 v51, v197, v50
	v_lshl_add_u64 v[56:57], v[102:103], 1, s[24:25]
	global_store_dwordx4 v[56:57], v[52:55], off
	s_and_saveexec_b64 s[8:9], s[2:3]
	s_cbranch_execz .LBB0_1606
	s_waitcnt lgkmcnt(0)
	v_add_f32_e32 v50, v50, v51
	ds_write_b32 v192, v50 offset:256

; #define LAS __attribute__((address_space(3)))
;     DEVI f32x4 load(int r, int c) const { const bf16x4 y = *(const bf16x4*)(Y + (size_t)r * DM + c); return (f32x4){bf2f((u16)y[0]), bf2f((u16)y[1]), bf2f((u16)y[2]), bf2f((u16)y[3])}; }
; template <class Epi>
; DEVI void gemm_phase(LAS unsigned char* lds, const Gemm g, const Epi& E) {
;     ...
;                             for (int n = 0; n < 2; ++n) pre[m][bj][n] = E.load(row0 + ai * HALF + (m0 + m) * 16, col0 + bj * HALF + n * NST);
;                 }
; #pragma unroll
;                 for (int mm = 0; mm < 2; ++mm) {
;                     const int m = m0 + mm;
;                     const int r = row0 + ai * HALF + m * 16; float rs = 1.f, part = 0.f;
;                     if constexpr (Epi::RS) rs = rsv[ai * 4 + m];
;                     if constexpr (Epi::PAIR) E.pair8(cur.b, r, cur.pn * HALF + wc * 32 + 8 * fq, acc[ai][0][m][0] * rs, acc[ai][0][m][1] * rs, acc[ai][1][m][0] * rs, acc[ai][1][m][1] * rs);
;                     else
; #pragma unroll
;                     for (int bj = 0; bj < 2; ++bj) {
;                         const int c = col0 + bj * HALF; f32x4 v0 = acc[ai][bj][m][0], v1 = acc[ai][bj][m][1];
;                         if constexpr (Epi::RS) { v0 = v0 * rs; v1 = v1 * rs; }
;                         if constexpr (Epi::PRE) part += E.frag_pre8(cur.b, r, c, v0, v1, pre[mm][bj][0], pre[mm][bj][1]);
;                         else if constexpr (Epi::PERM) E.frag8(cur.b, r, c, v0, v1);
;                         else { E.frag(cur.b, r, c, v0); E.frag(cur.b, r, c + 16, v1); }
;                     }
;                     if constexpr (Epi::SSQ) { part += __shfl_xor(part, 16); part += __shfl_xor(part, 32); if (fq == 0) ((LAS float*)(lds + 131072))[(wr * 4 + wc) * 128 + ai * 64 + m * 16 + fr] = part; }
.LBB0_1608:
	s_or_b64 exec, exec, s[8:9]
	v_add_u32_e32 v70, 0xa0, v182
	v_ashrrev_i32_e32 v71, 31, v70
	s_waitcnt lgkmcnt(0)
	v_lshlrev_b64 v[34:35], 12, v[70:71]
	v_lshl_add_u64 v[34:35], s[30:31], 0, v[34:35]
	v_lshl_add_u64 v[72:73], v[34:35], 0, v[184:185]
	global_load_dwordx4 v[54:57], v[72:73], off nt
	global_load_dwordx4 v[58:61], v[72:73], off offset:16 nt
	global_load_dwordx4 v[62:65], v[72:73], off offset:512 nt
	global_load_dwordx4 v[66:69], v[72:73], off offset:528 nt
	v_add_u32_e32 v52, 0xb0, v182
	v_ashrrev_i32_e32 v53, 31, v52
	v_lshlrev_b64 v[34:35], 12, v[52:53]
	v_lshl_add_u64 v[34:35], s[30:31], 0, v[34:35]
	v_lshl_add_u64 v[50:51], v[34:35], 0, v[184:185]
	global_load_dwordx4 v[42:45], v[50:51], off offset:16
	global_load_dwordx4 v[46:49], v[50:51], off
	global_load_dwordx4 v[34:37], v[50:51], off offset:528
	global_load_dwordx4 v[38:41], v[50:51], off offset:512
	v_lshlrev_b64 v[70:71], 10, v[70:71]
	v_lshl_add_u64 v[74:75], v[70:71], 0, v[180:181]
	v_lshl_add_u64 v[74:75], v[74:75], 1, s[24:25]
	v_lshl_add_u64 v[70:71], v[70:71], 0, v[178:179]
	s_waitcnt vmcnt(7)
	v_pk_add_f32 v[32:33], v[32:33], v[56:57]
	v_pk_add_f32 v[30:31], v[30:31], v[54:55]
	s_waitcnt vmcnt(6)
	v_pk_add_f32 v[28:29], v[28:29], v[60:61]
	v_pk_add_f32 v[26:27], v[26:27], v[58:59]
	s_waitcnt vmcnt(5)
	v_pk_add_f32 v[24:25], v[24:25], v[64:65]
	v_pk_add_f32 v[22:23], v[22:23], v[62:63]
	s_waitcnt vmcnt(4)
	v_pk_add_f32 v[56:57], v[20:21], v[68:69]
	v_pk_add_f32 v[54:55], v[18:19], v[66:67]
	global_store_dwordx4 v[72:73], v[30:33], off nt
	global_store_dwordx4 v[72:73], v[26:29], off offset:16 nt
	v_cvt_pk_bf16_f32 v18, v30, v31
	v_cvt_pk_bf16_f32 v19, v32, v33
	v_cvt_pk_bf16_f32 v20, v26, v27
	v_cvt_pk_bf16_f32 v21, v28, v29
	v_mul_f32_e32 v31, v31, v31
	v_mul_f32_e32 v33, v33, v33
	v_mul_f32_e32 v27, v27, v27
	v_mul_f32_e32 v29, v29, v29
	v_mul_f32_e32 v58, v23, v23
	v_mul_f32_e32 v59, v25, v25
	v_mul_f32_e32 v60, v55, v55
	v_mul_f32_e32 v61, v57, v57
	v_fmac_f32_e32 v31, v30, v30
	v_fmac_f32_e32 v33, v32, v32
	v_fmac_f32_e32 v27, v26, v26
	v_fmac_f32_e32 v29, v28, v28
	v_fmac_f32_e32 v58, v22, v22
	v_fmac_f32_e32 v59, v24, v24
	v_fmac_f32_e32 v60, v54, v54
	v_fmac_f32_e32 v61, v56, v56
	global_store_dwordx4 v[74:75], v[18:21], off
	global_store_dwordx4 v[72:73], v[22:25], off offset:512 nt
	global_store_dwordx4 v[72:73], v[54:57], off offset:528 nt
	v_add_f32_e32 v18, v31, v33
	v_add_f32_e32 v19, v27, v29
	v_add_f32_e32 v20, v58, v59
	v_add_f32_e32 v21, v60, v61
	v_add_f32_e32 v18, v18, v19
	v_add_f32_e32 v19, v20, v21
	v_add_f32_e32 v18, v18, v19
	ds_bpermute_b32 v19, v198, v18
	v_cvt_pk_bf16_f32 v20, v22, v23
	v_cvt_pk_bf16_f32 v21, v24, v25
	v_cvt_pk_bf16_f32 v22, v54, v55
	v_cvt_pk_bf16_f32 v23, v56, v57
	s_waitcnt lgkmcnt(0)
	v_add_f32_e32 v18, v18, v19
	ds_bpermute_b32 v19, v197, v18
	v_lshl_add_u64 v[24:25], v[70:71], 1, s[24:25]
	global_store_dwordx4 v[24:25], v[20:23], off
	s_and_saveexec_b64 s[8:9], s[2:3]
	s_cbranch_execz .LBB0_1610
	s_waitcnt lgkmcnt(0)
	v_add_f32_e32 v18, v18, v19
	ds_write_b32 v192, v18 offset:384

; #define PG8_STAGE(bufoff, gbase, voff) do { _Pragma("unroll") for (int _i = 0; _i < 2; ++_i) \
;         __builtin_amdgcn_global_load_lds((const unsigned*)((const char*)(gbase) + (voff)[_i]), (LAS unsigned*)(lds + (bufoff) + ldsw + _i * 8192), 16, 0, 0); } while (0)
; #define PG8_LDA(dst, b, h) do { _Pragma("unroll") for (int m = 0; m < 4; ++m) _Pragma("unroll") for (int k = 0; k < 2; ++k) dst[m][k] = *(const LAS bf16x8*)(lds + PG8_SA(b, h) + aoff + m * 2048 + k * 1024); } while (0)
; #define PG8_LDB(dst, b, h) do { _Pragma("unroll") for (int n = 0; n < 2; ++n) _Pragma("unroll") for (int k = 0; k < 2; ++k) dst[n][k] = *(const LAS bf16x8*)(lds + PG8_SB(b, h) + boff + n * 2048 + k * 1024); } while (0)
; #define PG8_MMA(ai, bj, At, Bt) do { __builtin_amdgcn_s_setprio(1); _Pragma("unroll") for (int m = 0; m < 4; ++m) _Pragma("unroll") for (int n = 0; n < 2; ++n) _Pragma("unroll") for (int k = 0; k < 2; ++k) \
;         acc[ai][bj][m][n] = __builtin_amdgcn_mfma_f32_16x16x32_bf16(Bt[n][k], At[m][k], acc[ai][bj][m][n], 0, 0, 0); __builtin_amdgcn_s_setprio(0); } while (0)
; #define PG8_WAIT_L(n) asm volatile("s_waitcnt lgkmcnt(" #n ")" ::: "memory")
; #define PG8_BAR __builtin_amdgcn_s_barrier()
; #define PG8_SCHED __builtin_amdgcn_sched_barrier(0)
; template <class Epi>
; DEVI void gemm_phase(LAS unsigned char* lds, const Gemm g, const Epi& E) {
;     ...
;         for (int t = 0; t < nt; t += 2) {
;             const bool last = (t == nt - 2);
;             const char* a1 = cA + (size_t)(t + 1) * kstep;
;             const char* a2 = last ? nA : cA + (size_t)(t + 2) * kstep; const char* b2 = last ? nB : cB + (size_t)(t + 2) * kstep;
;             const char* a3 = a2 + kstep; const char* b3 = b2 + kstep;
;             PG8_LDB(B0, 0, 0); PG8_SCHED; PG8_LDA(At, 0, 0); PG8_STAGE(PG8_SA(1, 1), a1 + hstepA, voffA);
;             PG8_WAIT_L(8); PG8_BAR; PG8_WAIT_L(0); PG8_MMA(0, 0, At, B0); PG8_BAR; PG8_SCHED;
;             PG8_LDB(B1, 0, 1); PG8_STAGE(PG8_SB(0, 0), b2, voffB);
;             PG8_BAR; PG8_WAIT_L(0); PG8_MMA(0, 1, At, B1); PG8_BAR;
;             PG8_LDA(At, 0, 1); PG8_STAGE(PG8_SA(0, 0), a2, voffA);
;             PG8_BAR; PG8_WAIT_L(0); PG8_MMA(1, 0, At, B0); PG8_BAR; PG8_SCHED;
.LBB0_1747:
	s_add_u32 s36, s16, 0x100
	s_addc_u32 s37, s17, 0
	s_add_i32 s19, 0, 0x10000
	v_add_u32_e32 v142, s19, v191
	ds_read_b128 v[130:133], v142
	ds_read_b128 v[134:137], v142 offset:1024
	ds_read_b128 v[138:141], v142 offset:2048
	ds_read_b128 v[142:145], v142 offset:3072
	s_cmp_eq_u32 s18, 40
	s_cselect_b32 s69, s9, s37
	s_cselect_b32 s68, s8, s36
	s_cselect_b32 s47, s11, s13
	s_cselect_b32 s46, s10, s1
	v_lshl_add_u64 v[162:163], s[16:17], 0, v[152:153]
	s_add_i32 m0, s81, 0xc000
	ds_read_b128 v[178:181], v196
	ds_read_b128 v[182:185], v196 offset:1024
	ds_read_b128 v[186:189], v196 offset:2048
	ds_read_b128 v[198:201], v196 offset:3072
	ds_read_b128 v[202:205], v196 offset:4096
	ds_read_b128 v[206:209], v196 offset:5120
	ds_read_b128 v[214:217], v196 offset:6144
	ds_read_b128 v[218:221], v196 offset:7168
	global_load_lds_dwordx4 v[162:163], off
	s_add_i32 m0, s81, 0xe000
	v_lshl_add_u64 v[162:163], s[16:17], 0, v[176:177]
	global_load_lds_dwordx4 v[162:163], off
	s_waitcnt lgkmcnt(8)
	s_barrier
	s_waitcnt lgkmcnt(0)
	v_mfma_f32_16x16x32_bf16 v[126:129], v[130:133], v[178:181], v[126:129]
	v_mfma_f32_16x16x32_bf16 v[122:125], v[138:141], v[178:181], v[122:125]
	v_mfma_f32_16x16x32_bf16 v[110:113], v[130:133], v[186:189], v[110:113]
	v_mfma_f32_16x16x32_bf16 v[106:109], v[138:141], v[186:189], v[106:109]
	v_mfma_f32_16x16x32_bf16 v[94:97], v[130:133], v[202:205], v[94:97]
	v_mfma_f32_16x16x32_bf16 v[90:93], v[138:141], v[202:205], v[90:93]
	v_mfma_f32_16x16x32_bf16 v[78:81], v[130:133], v[214:217], v[78:81]
	v_mfma_f32_16x16x32_bf16 v[74:77], v[138:141], v[214:217], v[74:77]
	v_mfma_f32_16x16x32_bf16 v[126:129], v[134:137], v[182:185], v[126:129]
	v_mfma_f32_16x16x32_bf16 v[122:125], v[142:145], v[182:185], v[122:125]
	v_mfma_f32_16x16x32_bf16 v[110:113], v[134:137], v[198:201], v[110:113]
	v_mfma_f32_16x16x32_bf16 v[106:109], v[142:145], v[198:201], v[106:109]
	v_mfma_f32_16x16x32_bf16 v[94:97], v[134:137], v[206:209], v[94:97]
	v_mfma_f32_16x16x32_bf16 v[90:93], v[142:145], v[206:209], v[90:93]
	v_mfma_f32_16x16x32_bf16 v[78:81], v[134:137], v[218:221], v[78:81]
	v_mfma_f32_16x16x32_bf16 v[74:77], v[142:145], v[218:221], v[74:77]
	s_barrier
	s_add_i32 s26, 0, 0x14000
	v_add_u32_e32 v162, s26, v191
	s_add_i32 s16, s19, s80
	ds_read_b128 v[222:225], v162
	ds_read_b128 v[226:229], v162 offset:1024
	ds_read_b128 v[230:233], v162 offset:2048
	ds_read_b128 v[234:237], v162 offset:3072
	v_lshl_add_u64 v[162:163], s[46:47], 0, v[8:9]
	s_mov_b32 m0, s16
	v_lshl_add_u64 v[164:165], s[46:47], 0, v[150:151]
	global_load_lds_dwordx4 v[162:163], off
	s_add_i32 m0, s16, 0x2000
	s_nop 0
	global_load_lds_dwordx4 v[164:165], off
	s_barrier
	s_waitcnt lgkmcnt(0)
	v_mfma_f32_16x16x32_bf16 v[118:121], v[222:225], v[178:181], v[118:121]
	v_mfma_f32_16x16x32_bf16 v[114:117], v[230:233], v[178:181], v[114:117]
	v_mfma_f32_16x16x32_bf16 v[102:105], v[222:225], v[186:189], v[102:105]
	v_mfma_f32_16x16x32_bf16 v[98:101], v[230:233], v[186:189], v[98:101]
	v_mfma_f32_16x16x32_bf16 v[86:89], v[222:225], v[202:205], v[86:89]
	v_mfma_f32_16x16x32_bf16 v[82:85], v[230:233], v[202:205], v[82:85]
	v_mfma_f32_16x16x32_bf16 v[70:73], v[222:225], v[214:217], v[70:73]
	v_mfma_f32_16x16x32_bf16 v[66:69], v[230:233], v[214:217], v[66:69]
	v_mfma_f32_16x16x32_bf16 v[118:121], v[226:229], v[182:185], v[118:121]
	v_mfma_f32_16x16x32_bf16 v[114:117], v[234:237], v[182:185], v[114:117]
	v_mfma_f32_16x16x32_bf16 v[102:105], v[226:229], v[198:201], v[102:105]
	v_mfma_f32_16x16x32_bf16 v[98:101], v[234:237], v[198:201], v[98:101]
	v_mfma_f32_16x16x32_bf16 v[86:89], v[226:229], v[206:209], v[86:89]
	v_mfma_f32_16x16x32_bf16 v[82:85], v[234:237], v[206:209], v[82:85]
	v_mfma_f32_16x16x32_bf16 v[70:73], v[226:229], v[218:221], v[70:73]
	v_mfma_f32_16x16x32_bf16 v[66:69], v[234:237], v[218:221], v[66:69]
	s_mov_b32 m0, s81
	v_lshl_add_u64 v[238:239], s[68:69], 0, v[146:147]
	s_barrier
	ds_read_b128 v[178:181], v196 offset:16384
	ds_read_b128 v[182:185], v196 offset:17408
	ds_read_b128 v[186:189], v196 offset:18432
	ds_read_b128 v[198:201], v196 offset:19456
	ds_read_b128 v[202:205], v196 offset:20480
	ds_read_b128 v[206:209], v196 offset:21504
	ds_read_b128 v[214:217], v196 offset:22528
	ds_read_b128 v[218:221], v196 offset:23552
	global_load_lds_dwordx4 v[238:239], off
	s_mov_b32 m0, s82
	v_lshl_add_u64 v[240:241], s[68:69], 0, v[148:149]
	global_load_lds_dwordx4 v[240:241], off
	s_barrier
	s_waitcnt lgkmcnt(0)
	v_mfma_f32_16x16x32_bf16 v[62:65], v[130:133], v[178:181], v[62:65]
	v_mfma_f32_16x16x32_bf16 v[58:61], v[138:141], v[178:181], v[58:61]
	v_mfma_f32_16x16x32_bf16 v[46:49], v[130:133], v[186:189], v[46:49]
	v_mfma_f32_16x16x32_bf16 v[42:45], v[138:141], v[186:189], v[42:45]
	v_mfma_f32_16x16x32_bf16 v[30:33], v[130:133], v[202:205], v[30:33]
	v_mfma_f32_16x16x32_bf16 v[26:29], v[138:141], v[202:205], v[26:29]
	v_mfma_f32_16x16x32_bf16 v[14:17], v[130:133], v[214:217], v[14:17]
	v_mfma_f32_16x16x32_bf16 v[10:13], v[138:141], v[214:217], v[10:13]
	v_mfma_f32_16x16x32_bf16 v[62:65], v[134:137], v[182:185], v[62:65]
	v_mfma_f32_16x16x32_bf16 v[58:61], v[142:145], v[182:185], v[58:61]
	v_mfma_f32_16x16x32_bf16 v[46:49], v[134:137], v[198:201], v[46:49]
	v_mfma_f32_16x16x32_bf16 v[42:45], v[142:145], v[198:201], v[42:45]
	v_mfma_f32_16x16x32_bf16 v[30:33], v[134:137], v[206:209], v[30:33]
	v_mfma_f32_16x16x32_bf16 v[26:29], v[142:145], v[206:209], v[26:29]
	v_mfma_f32_16x16x32_bf16 v[14:17], v[134:137], v[218:221], v[14:17]
	v_mfma_f32_16x16x32_bf16 v[10:13], v[142:145], v[218:221], v[10:13]
	s_barrier
; #define PG8_STAGE(bufoff, gbase, voff) do { _Pragma("unroll") for (int _i = 0; _i < 2; ++_i) \
;         __builtin_amdgcn_global_load_lds((const unsigned*)((const char*)(gbase) + (voff)[_i]), (LAS unsigned*)(lds + (bufoff) + ldsw + _i * 8192), 16, 0, 0); } while (0)
; #define PG8_LDA(dst, b, h) do { _Pragma("unroll") for (int m = 0; m < 4; ++m) _Pragma("unroll") for (int k = 0; k < 2; ++k) dst[m][k] = *(const LAS bf16x8*)(lds + PG8_SA(b, h) + aoff + m * 2048 + k * 1024); } while (0)
; #define PG8_LDB(dst, b, h) do { _Pragma("unroll") for (int n = 0; n < 2; ++n) _Pragma("unroll") for (int k = 0; k < 2; ++k) dst[n][k] = *(const LAS bf16x8*)(lds + PG8_SB(b, h) + boff + n * 2048 + k * 1024); } while (0)
; #define PG8_MMA(ai, bj, At, Bt) do { __builtin_amdgcn_s_setprio(1); _Pragma("unroll") for (int m = 0; m < 4; ++m) _Pragma("unroll") for (int n = 0; n < 2; ++n) _Pragma("unroll") for (int k = 0; k < 2; ++k) \
;         acc[ai][bj][m][n] = __builtin_amdgcn_mfma_f32_16x16x32_bf16(Bt[n][k], At[m][k], acc[ai][bj][m][n], 0, 0, 0); __builtin_amdgcn_s_setprio(0); } while (0)
; #define PG8_WAIT_V(n) asm volatile("s_waitcnt vmcnt(" #n ")" ::: "memory")
; #define PG8_WAIT_L(n) asm volatile("s_waitcnt lgkmcnt(" #n ")" ::: "memory")
; #define PG8_BAR __builtin_amdgcn_s_barrier()
; #define PG8_SCHED __builtin_amdgcn_sched_barrier(0)
; template <class Epi>
; DEVI void gemm_phase(LAS unsigned char* lds, const Gemm g, const Epi& E) {
;     ...
;             PG8_STAGE(PG8_SB(0, 1), b2 + hstepB, voffB);
;             PG8_WAIT_V(6); PG8_BAR; PG8_MMA(1, 1, At, B1); PG8_BAR;
;             PG8_LDB(B0, 1, 0); PG8_SCHED; PG8_LDA(At, 1, 0); PG8_STAGE(PG8_SA(0, 1), a2 + hstepA, voffA);
;             PG8_WAIT_L(8); PG8_BAR; PG8_WAIT_L(0); PG8_MMA(0, 0, At, B0); PG8_BAR; PG8_SCHED;
;             PG8_LDB(B1, 1, 1); PG8_STAGE(PG8_SB(1, 0), b3, voffB);
;             PG8_BAR; PG8_WAIT_L(0); PG8_MMA(0, 1, At, B1); PG8_BAR;
;             PG8_LDA(At, 1, 1); PG8_STAGE(PG8_SA(1, 0), a3, voffA);
;             PG8_BAR; PG8_WAIT_L(0); PG8_MMA(1, 0, At, B0); PG8_BAR; PG8_SCHED;
;             PG8_STAGE(PG8_SB(1, 1), b3 + hstepB, voffB);
;             PG8_WAIT_V(6); PG8_BAR; PG8_MMA(1, 1, At, B1); PG8_BAR;
	s_add_u32 s16, s46, 0xb0000
	s_addc_u32 s17, s47, 0
	s_add_i32 s19, s26, s80
	s_mov_b32 m0, s19
	v_lshl_add_u64 v[130:131], s[16:17], 0, v[8:9]
	global_load_lds_dwordx4 v[130:131], off
	s_add_i32 m0, s19, 0x2000
	v_lshl_add_u64 v[130:131], s[16:17], 0, v[150:151]
	global_load_lds_dwordx4 v[130:131], off
	s_waitcnt vmcnt(6)
	s_barrier
	v_mfma_f32_16x16x32_bf16 v[54:57], v[222:225], v[178:181], v[54:57]
	v_mfma_f32_16x16x32_bf16 v[50:53], v[230:233], v[178:181], v[50:53]
	v_mfma_f32_16x16x32_bf16 v[38:41], v[222:225], v[186:189], v[38:41]
	v_mfma_f32_16x16x32_bf16 v[34:37], v[230:233], v[186:189], v[34:37]
	v_mfma_f32_16x16x32_bf16 v[22:25], v[222:225], v[202:205], v[22:25]
	v_mfma_f32_16x16x32_bf16 v[18:21], v[230:233], v[202:205], v[18:21]
	v_mfma_f32_16x16x32_bf16 v[4:7], v[222:225], v[214:217], v[4:7]
	v_mfma_f32_16x16x32_bf16 v[0:3], v[230:233], v[214:217], v[0:3]
	v_mfma_f32_16x16x32_bf16 v[54:57], v[226:229], v[182:185], v[54:57]
	v_mfma_f32_16x16x32_bf16 v[50:53], v[234:237], v[182:185], v[50:53]
	v_mfma_f32_16x16x32_bf16 v[38:41], v[226:229], v[198:201], v[38:41]
	v_mfma_f32_16x16x32_bf16 v[34:37], v[234:237], v[198:201], v[34:37]
	v_mfma_f32_16x16x32_bf16 v[22:25], v[226:229], v[206:209], v[22:25]
	v_mfma_f32_16x16x32_bf16 v[18:21], v[234:237], v[206:209], v[18:21]
	v_mfma_f32_16x16x32_bf16 v[4:7], v[226:229], v[218:221], v[4:7]
	v_mfma_f32_16x16x32_bf16 v[0:3], v[234:237], v[218:221], v[0:3]
	s_add_i32 s19, 0, 0x18000
	v_add_u32_e32 v142, s19, v191
	s_barrier
	ds_read_b128 v[130:133], v142
	ds_read_b128 v[134:137], v142 offset:1024
	ds_read_b128 v[138:141], v142 offset:2048
	ds_read_b128 v[142:145], v142 offset:3072
	s_add_u32 s16, s68, 0xb0000
	s_addc_u32 s17, s69, 0
	s_mov_b32 m0, s83
	v_lshl_add_u64 v[222:223], s[16:17], 0, v[146:147]
	ds_read_b128 v[178:181], v196 offset:32768
	ds_read_b128 v[182:185], v196 offset:33792
	ds_read_b128 v[186:189], v196 offset:34816
	ds_read_b128 v[198:201], v196 offset:35840
	ds_read_b128 v[202:205], v196 offset:36864
	ds_read_b128 v[206:209], v196 offset:37888
	ds_read_b128 v[214:217], v196 offset:38912
	ds_read_b128 v[218:221], v196 offset:39936
	global_load_lds_dwordx4 v[222:223], off
	s_mov_b32 m0, s84
	v_lshl_add_u64 v[222:223], s[16:17], 0, v[148:149]
	global_load_lds_dwordx4 v[222:223], off
	s_waitcnt lgkmcnt(8)
	s_barrier
	s_waitcnt lgkmcnt(0)
	v_mfma_f32_16x16x32_bf16 v[126:129], v[130:133], v[178:181], v[126:129]
	v_mfma_f32_16x16x32_bf16 v[122:125], v[138:141], v[178:181], v[122:125]
	v_mfma_f32_16x16x32_bf16 v[110:113], v[130:133], v[186:189], v[110:113]
	v_mfma_f32_16x16x32_bf16 v[106:109], v[138:141], v[186:189], v[106:109]
	v_mfma_f32_16x16x32_bf16 v[94:97], v[130:133], v[202:205], v[94:97]
	v_mfma_f32_16x16x32_bf16 v[90:93], v[138:141], v[202:205], v[90:93]
	v_mfma_f32_16x16x32_bf16 v[78:81], v[130:133], v[214:217], v[78:81]
	v_mfma_f32_16x16x32_bf16 v[74:77], v[138:141], v[214:217], v[74:77]
	v_mfma_f32_16x16x32_bf16 v[126:129], v[134:137], v[182:185], v[126:129]
	v_mfma_f32_16x16x32_bf16 v[122:125], v[142:145], v[182:185], v[122:125]
	v_mfma_f32_16x16x32_bf16 v[110:113], v[134:137], v[198:201], v[110:113]
	v_mfma_f32_16x16x32_bf16 v[106:109], v[142:145], v[198:201], v[106:109]
	v_mfma_f32_16x16x32_bf16 v[94:97], v[134:137], v[206:209], v[94:97]
	v_mfma_f32_16x16x32_bf16 v[90:93], v[142:145], v[206:209], v[90:93]
	v_mfma_f32_16x16x32_bf16 v[78:81], v[134:137], v[218:221], v[78:81]
	v_mfma_f32_16x16x32_bf16 v[74:77], v[142:145], v[218:221], v[74:77]
	s_barrier
	s_add_i32 s26, 0, 0x1c000
	s_add_i32 s16, s19, s80
	v_add_u32_e32 v197, s26, v191
	v_lshl_add_u64 v[162:163], v[162:163], 0, s[70:71]
	s_mov_b32 m0, s16
	ds_read_b128 v[222:225], v197
	ds_read_b128 v[226:229], v197 offset:1024
	ds_read_b128 v[230:233], v197 offset:2048
	ds_read_b128 v[234:237], v197 offset:3072
	global_load_lds_dwordx4 v[162:163], off
	s_add_i32 m0, s16, 0x2000
	v_lshl_add_u64 v[162:163], v[164:165], 0, s[70:71]
	global_load_lds_dwordx4 v[162:163], off
	s_barrier
	s_waitcnt lgkmcnt(0)
	v_mfma_f32_16x16x32_bf16 v[118:121], v[222:225], v[178:181], v[118:121]
	v_mfma_f32_16x16x32_bf16 v[114:117], v[230:233], v[178:181], v[114:117]
	v_mfma_f32_16x16x32_bf16 v[102:105], v[222:225], v[186:189], v[102:105]
	v_mfma_f32_16x16x32_bf16 v[98:101], v[230:233], v[186:189], v[98:101]
	v_mfma_f32_16x16x32_bf16 v[86:89], v[222:225], v[202:205], v[86:89]
	v_mfma_f32_16x16x32_bf16 v[82:85], v[230:233], v[202:205], v[82:85]
	v_mfma_f32_16x16x32_bf16 v[70:73], v[222:225], v[214:217], v[70:73]
	v_mfma_f32_16x16x32_bf16 v[66:69], v[230:233], v[214:217], v[66:69]
	v_mfma_f32_16x16x32_bf16 v[118:121], v[226:229], v[182:185], v[118:121]
	v_mfma_f32_16x16x32_bf16 v[114:117], v[234:237], v[182:185], v[114:117]
	v_mfma_f32_16x16x32_bf16 v[102:105], v[226:229], v[198:201], v[102:105]
	v_mfma_f32_16x16x32_bf16 v[98:101], v[234:237], v[198:201], v[98:101]
	v_mfma_f32_16x16x32_bf16 v[86:89], v[226:229], v[206:209], v[86:89]
	v_mfma_f32_16x16x32_bf16 v[82:85], v[234:237], v[206:209], v[82:85]
	v_mfma_f32_16x16x32_bf16 v[70:73], v[226:229], v[218:221], v[70:73]
	v_mfma_f32_16x16x32_bf16 v[66:69], v[234:237], v[218:221], v[66:69]
	s_mov_b32 m0, s76
	v_lshl_add_u64 v[162:163], v[238:239], 0, s[70:71]
	s_barrier
	ds_read_b128 v[178:181], v196 offset:49152
	ds_read_b128 v[182:185], v196 offset:50176
	ds_read_b128 v[186:189], v196 offset:51200
	ds_read_b128 v[198:201], v196 offset:52224
	ds_read_b128 v[202:205], v196 offset:53248
	ds_read_b128 v[206:209], v196 offset:54272
	ds_read_b128 v[214:217], v196 offset:55296
	ds_read_b128 v[218:221], v196 offset:56320
	global_load_lds_dwordx4 v[162:163], off
	s_mov_b32 m0, s77
	v_lshl_add_u64 v[162:163], v[240:241], 0, s[70:71]
	global_load_lds_dwordx4 v[162:163], off
	s_barrier
; #define LAS __attribute__((address_space(3)))
;     DEVI f32x4 load(int r, int c) const { const bf16x4 y = *(const bf16x4*)(Y + (size_t)r * DM + c); return (f32x4){bf2f((u16)y[0]), bf2f((u16)y[1]), bf2f((u16)y[2]), bf2f((u16)y[3])}; }
; template <class Epi>
; DEVI void gemm_phase(LAS unsigned char* lds, const Gemm g, const Epi& E) {
;     ...
;             for (int am = 0; am < 4; ++am) {
;                 const int ai = am >> 1, m0 = (am & 1) * 2;
;                 f32x4 pre[2][2][2];
;                 if constexpr (Epi::PRE) {
; #pragma unroll
;                     for (int m = 0; m < 2; ++m)
; #pragma unroll
;                         for (int bj = 0; bj < 2; ++bj)
; #pragma unroll
;                             for (int n = 0; n < 2; ++n) pre[m][bj][n] = E.load(row0 + ai * HALF + (m0 + m) * 16, col0 + bj * HALF + n * NST);
;                 }
; #pragma unroll
;                 for (int mm = 0; mm < 2; ++mm) {
;                     const int m = m0 + mm;
;                     const int r = row0 + ai * HALF + m * 16; float rs = 1.f, part = 0.f;
;                     if constexpr (Epi::RS) rs = rsv[ai * 4 + m];
;                     if constexpr (Epi::PAIR) E.pair8(cur.b, r, cur.pn * HALF + wc * 32 + 8 * fq, acc[ai][0][m][0] * rs, acc[ai][0][m][1] * rs, acc[ai][1][m][0] * rs, acc[ai][1][m][1] * rs);
;                     else
; #pragma unroll
;                     for (int bj = 0; bj < 2; ++bj) {
;                         const int c = col0 + bj * HALF; f32x4 v0 = acc[ai][bj][m][0], v1 = acc[ai][bj][m][1];
;                         if constexpr (Epi::RS) { v0 = v0 * rs; v1 = v1 * rs; }
;                         if constexpr (Epi::PRE) part += E.frag_pre8(cur.b, r, c, v0, v1, pre[mm][bj][0], pre[mm][bj][1]);
;                         else if constexpr (Epi::PERM) E.frag8(cur.b, r, c, v0, v1);
;                         else { E.frag(cur.b, r, c, v0); E.frag(cur.b, r, c + 16, v1); }
;                     }
;                     if constexpr (Epi::SSQ) { part += __shfl_xor(part, 16); part += __shfl_xor(part, 32); if (fq == 0) ((LAS float*)(lds + 131072))[(wr * 4 + wc) * 128 + ai * 64 + m * 16 + fr] = part; }
	s_waitcnt lgkmcnt(0)
	v_mfma_f32_16x16x32_bf16 v[62:65], v[130:133], v[178:181], v[62:65]
	v_mfma_f32_16x16x32_bf16 v[58:61], v[138:141], v[178:181], v[58:61]
	v_mfma_f32_16x16x32_bf16 v[46:49], v[130:133], v[186:189], v[46:49]
	v_mfma_f32_16x16x32_bf16 v[42:45], v[138:141], v[186:189], v[42:45]
	v_mfma_f32_16x16x32_bf16 v[30:33], v[130:133], v[202:205], v[30:33]
	v_mfma_f32_16x16x32_bf16 v[26:29], v[138:141], v[202:205], v[26:29]
	v_mfma_f32_16x16x32_bf16 v[14:17], v[130:133], v[214:217], v[14:17]
	v_mfma_f32_16x16x32_bf16 v[10:13], v[138:141], v[214:217], v[10:13]
	v_mfma_f32_16x16x32_bf16 v[62:65], v[134:137], v[182:185], v[62:65]
	v_mfma_f32_16x16x32_bf16 v[58:61], v[142:145], v[182:185], v[58:61]
	v_mfma_f32_16x16x32_bf16 v[46:49], v[134:137], v[198:201], v[46:49]
	v_mfma_f32_16x16x32_bf16 v[42:45], v[142:145], v[198:201], v[42:45]
	v_mfma_f32_16x16x32_bf16 v[30:33], v[134:137], v[206:209], v[30:33]
	v_mfma_f32_16x16x32_bf16 v[26:29], v[142:145], v[206:209], v[26:29]
	v_mfma_f32_16x16x32_bf16 v[14:17], v[134:137], v[218:221], v[14:17]
	v_mfma_f32_16x16x32_bf16 v[10:13], v[142:145], v[218:221], v[10:13]
	s_barrier
	s_add_u32 s16, s46, 0xb0080
	s_addc_u32 s17, s47, 0
	s_add_i32 s19, s26, s80
	s_mov_b32 m0, s19
	v_lshl_add_u64 v[130:131], s[16:17], 0, v[8:9]
	global_load_lds_dwordx4 v[130:131], off
	s_add_i32 m0, s19, 0x2000
	v_lshl_add_u64 v[130:131], s[16:17], 0, v[150:151]
	global_load_lds_dwordx4 v[130:131], off
	s_waitcnt vmcnt(6)
	s_barrier
	v_mfma_f32_16x16x32_bf16 v[54:57], v[222:225], v[178:181], v[54:57]
	v_mfma_f32_16x16x32_bf16 v[50:53], v[230:233], v[178:181], v[50:53]
	v_mfma_f32_16x16x32_bf16 v[38:41], v[222:225], v[186:189], v[38:41]
	v_mfma_f32_16x16x32_bf16 v[34:37], v[230:233], v[186:189], v[34:37]
	v_mfma_f32_16x16x32_bf16 v[22:25], v[222:225], v[202:205], v[22:25]
	v_mfma_f32_16x16x32_bf16 v[18:21], v[230:233], v[202:205], v[18:21]
	v_mfma_f32_16x16x32_bf16 v[4:7], v[222:225], v[214:217], v[4:7]
	v_mfma_f32_16x16x32_bf16 v[0:3], v[230:233], v[214:217], v[0:3]
	v_mfma_f32_16x16x32_bf16 v[54:57], v[226:229], v[182:185], v[54:57]
	v_mfma_f32_16x16x32_bf16 v[50:53], v[234:237], v[182:185], v[50:53]
	v_mfma_f32_16x16x32_bf16 v[38:41], v[226:229], v[198:201], v[38:41]
	v_mfma_f32_16x16x32_bf16 v[34:37], v[234:237], v[198:201], v[34:37]
	v_mfma_f32_16x16x32_bf16 v[22:25], v[226:229], v[206:209], v[22:25]
	v_mfma_f32_16x16x32_bf16 v[18:21], v[234:237], v[206:209], v[18:21]
	v_mfma_f32_16x16x32_bf16 v[4:7], v[226:229], v[218:221], v[4:7]
	v_mfma_f32_16x16x32_bf16 v[0:3], v[234:237], v[218:221], v[0:3]
	s_add_i32 s18, s18, 2
	s_add_u32 s1, s1, 0x100
	s_addc_u32 s13, s13, 0
	s_cmp_gt_u32 s18, 41
	s_mov_b64 s[16:17], s[36:37]
	s_barrier
	s_cbranch_scc0 .LBB0_1747
	s_setprio 0
	s_lshl_b32 s0, s0, 8
	v_add_u32_e32 v182, s0, v190
	v_lshl_or_b32 v180, s12, 8, v195
	v_ashrrev_i32_e32 v183, 31, v182
	v_lshlrev_b64 v[130:131], 12, v[182:183]
	v_ashrrev_i32_e32 v181, 31, v180
	v_lshl_add_u64 v[130:131], s[30:31], 0, v[130:131]
	v_lshlrev_b64 v[184:185], 2, v[180:181]
	v_lshl_add_u64 v[162:163], v[130:131], 0, v[184:185]
	global_load_dwordx4 v[200:203], v[162:163], off nt
	global_load_dwordx4 v[204:207], v[162:163], off offset:16 nt
	global_load_dwordx4 v[214:217], v[162:163], off offset:512 nt
	global_load_dwordx4 v[218:221], v[162:163], off offset:528 nt
	v_or_b32_e32 v188, 16, v182
	v_ashrrev_i32_e32 v189, 31, v188
	v_lshlrev_b64 v[130:131], 12, v[188:189]
	v_lshl_add_u64 v[130:131], s[30:31], 0, v[130:131]
	v_lshl_add_u64 v[186:187], v[130:131], 0, v[184:185]
	global_load_dwordx4 v[138:141], v[186:187], off offset:16
	global_load_dwordx4 v[142:145], v[186:187], off
	global_load_dwordx4 v[130:133], v[186:187], off offset:528
	global_load_dwordx4 v[134:137], v[186:187], off offset:512
	v_and_b32_e32 v165, 64, v155
	v_xor_b32_e32 v164, 16, v155
	v_add_u32_e32 v165, 64, v165
	v_xor_b32_e32 v179, 32, v155
	v_cmp_lt_i32_e32 vcc, v164, v165
	v_or_b32_e32 v178, 0x80, v180
	s_waitcnt vmcnt(0)
	v_pk_add_f32 v[128:129], v[128:129], v[202:203]
	v_cndmask_b32_e32 v164, v155, v164, vcc
	v_cmp_lt_i32_e32 vcc, v179, v165
	v_lshlrev_b32_e32 v198, 2, v164
	v_pk_add_f32 v[126:127], v[126:127], v[200:201]
	v_cndmask_b32_e32 v165, v155, v179, vcc
	v_lshlrev_b32_e32 v197, 2, v165
	v_lshlrev_b64 v[164:165], 10, v[182:183]
	v_pk_add_f32 v[124:125], v[124:125], v[206:207]
	v_pk_add_f32 v[122:123], v[122:123], v[204:205]
	v_pk_add_f32 v[120:121], v[120:121], v[216:217]
	v_pk_add_f32 v[118:119], v[118:119], v[214:215]
	v_pk_add_f32 v[202:203], v[116:117], v[220:221]
	v_pk_add_f32 v[200:201], v[114:115], v[218:219]
	v_lshl_add_u64 v[208:209], v[164:165], 0, v[180:181]
	global_store_dwordx4 v[162:163], v[126:129], off nt
	global_store_dwordx4 v[162:163], v[122:125], off offset:16 nt
	v_cvt_pk_bf16_f32 v114, v126, v127
	v_cvt_pk_bf16_f32 v115, v128, v129
	v_cvt_pk_bf16_f32 v116, v122, v123
	v_cvt_pk_bf16_f32 v117, v124, v125
	v_mul_f32_e32 v127, v127, v127
	v_mul_f32_e32 v129, v129, v129
	v_mul_f32_e32 v123, v123, v123
	v_mul_f32_e32 v125, v125, v125
	v_mul_f32_e32 v183, v119, v119
	v_mul_f32_e32 v199, v121, v121
	v_mul_f32_e32 v204, v201, v201
	v_mul_f32_e32 v205, v203, v203
	v_lshl_add_u64 v[208:209], v[208:209], 1, s[24:25]
	v_fmac_f32_e32 v127, v126, v126
	v_fmac_f32_e32 v129, v128, v128
	v_fmac_f32_e32 v123, v122, v122
	v_fmac_f32_e32 v125, v124, v124
	v_fmac_f32_e32 v183, v118, v118
	v_fmac_f32_e32 v199, v120, v120
	v_fmac_f32_e32 v204, v200, v200
	v_fmac_f32_e32 v205, v202, v202
	global_store_dwordx4 v[208:209], v[114:117], off
	v_ashrrev_i32_e32 v179, 31, v178
	v_lshl_add_u64 v[164:165], v[164:165], 0, v[178:179]
	v_add_f32_e32 v114, v127, v129
	v_add_f32_e32 v115, v123, v125
	v_add_f32_e32 v116, v183, v199
	v_add_f32_e32 v117, v204, v205
	v_add_f32_e32 v114, v114, v115
	v_add_f32_e32 v115, v116, v117
	v_add_f32_e32 v114, v114, v115
	ds_bpermute_b32 v115, v198, v114
	global_store_dwordx4 v[162:163], v[118:121], off offset:512 nt
	global_store_dwordx4 v[162:163], v[200:203], off offset:528 nt
	v_cvt_pk_bf16_f32 v116, v118, v119
	v_cvt_pk_bf16_f32 v117, v120, v121
	v_cvt_pk_bf16_f32 v118, v200, v201
	s_waitcnt lgkmcnt(0)
	v_add_f32_e32 v114, v114, v115
	ds_bpermute_b32 v115, v197, v114
	v_cvt_pk_bf16_f32 v119, v202, v203
	v_lshl_add_u64 v[120:121], v[164:165], 1, s[24:25]
	global_store_dwordx4 v[120:121], v[116:119], off
	s_and_saveexec_b64 s[16:17], s[2:3]
	s_cbranch_execz .LBB0_1750
	s_waitcnt lgkmcnt(0)
	v_add_f32_e32 v114, v114, v115
	ds_write_b32 v192, v114

; #define LAS __attribute__((address_space(3)))
;     DEVI f32x4 load(int r, int c) const { const bf16x4 y = *(const bf16x4*)(Y + (size_t)r * DM + c); return (f32x4){bf2f((u16)y[0]), bf2f((u16)y[1]), bf2f((u16)y[2]), bf2f((u16)y[3])}; }
; template <class Epi>
; DEVI void gemm_phase(LAS unsigned char* lds, const Gemm g, const Epi& E) {
;     ...
;             for (int am = 0; am < 4; ++am) {
;                 const int ai = am >> 1, m0 = (am & 1) * 2;
;                 f32x4 pre[2][2][2];
;                 if constexpr (Epi::PRE) {
; #pragma unroll
;                     for (int m = 0; m < 2; ++m)
; #pragma unroll
;                         for (int bj = 0; bj < 2; ++bj)
; #pragma unroll
;                             for (int n = 0; n < 2; ++n) pre[m][bj][n] = E.load(row0 + ai * HALF + (m0 + m) * 16, col0 + bj * HALF + n * NST);
;                 }
; #pragma unroll
;                 for (int mm = 0; mm < 2; ++mm) {
;                     const int m = m0 + mm;
;                     const int r = row0 + ai * HALF + m * 16; float rs = 1.f, part = 0.f;
;                     if constexpr (Epi::RS) rs = rsv[ai * 4 + m];
;                     if constexpr (Epi::PAIR) E.pair8(cur.b, r, cur.pn * HALF + wc * 32 + 8 * fq, acc[ai][0][m][0] * rs, acc[ai][0][m][1] * rs, acc[ai][1][m][0] * rs, acc[ai][1][m][1] * rs);
;                     else
; #pragma unroll
;                     for (int bj = 0; bj < 2; ++bj) {
;                         const int c = col0 + bj * HALF; f32x4 v0 = acc[ai][bj][m][0], v1 = acc[ai][bj][m][1];
;                         if constexpr (Epi::RS) { v0 = v0 * rs; v1 = v1 * rs; }
;                         if constexpr (Epi::PRE) part += E.frag_pre8(cur.b, r, c, v0, v1, pre[mm][bj][0], pre[mm][bj][1]);
;                         else if constexpr (Epi::PERM) E.frag8(cur.b, r, c, v0, v1);
;                         else { E.frag(cur.b, r, c, v0); E.frag(cur.b, r, c + 16, v1); }
;                     }
;                     if constexpr (Epi::SSQ) { part += __shfl_xor(part, 16); part += __shfl_xor(part, 32); if (fq == 0) ((LAS float*)(lds + 131072))[(wr * 4 + wc) * 128 + ai * 64 + m * 16 + fr] = part; }
.LBB0_1752:
	s_or_b64 exec, exec, s[16:17]
	v_or_b32_e32 v134, 32, v182
	v_ashrrev_i32_e32 v135, 31, v134
	s_waitcnt lgkmcnt(0)
	v_lshlrev_b64 v[98:99], 12, v[134:135]
	v_lshl_add_u64 v[98:99], s[30:31], 0, v[98:99]
	v_lshl_add_u64 v[136:137], v[98:99], 0, v[184:185]
	global_load_dwordx4 v[118:121], v[136:137], off nt
	global_load_dwordx4 v[122:125], v[136:137], off offset:16 nt
	global_load_dwordx4 v[126:129], v[136:137], off offset:512 nt
	global_load_dwordx4 v[130:133], v[136:137], off offset:528 nt
	v_or_b32_e32 v116, 48, v182
	v_ashrrev_i32_e32 v117, 31, v116
	v_lshlrev_b64 v[98:99], 12, v[116:117]
	v_lshl_add_u64 v[98:99], s[30:31], 0, v[98:99]
	v_lshl_add_u64 v[114:115], v[98:99], 0, v[184:185]
	global_load_dwordx4 v[106:109], v[114:115], off offset:16
	global_load_dwordx4 v[110:113], v[114:115], off
	global_load_dwordx4 v[98:101], v[114:115], off offset:528
	global_load_dwordx4 v[102:105], v[114:115], off offset:512
	v_lshlrev_b64 v[134:135], 10, v[134:135]
	v_lshl_add_u64 v[138:139], v[134:135], 0, v[180:181]
	v_lshl_add_u64 v[138:139], v[138:139], 1, s[24:25]
	v_lshl_add_u64 v[134:135], v[134:135], 0, v[178:179]
	s_waitcnt vmcnt(7)
	v_pk_add_f32 v[96:97], v[96:97], v[120:121]
	v_pk_add_f32 v[94:95], v[94:95], v[118:119]
	s_waitcnt vmcnt(6)
	v_pk_add_f32 v[92:93], v[92:93], v[124:125]
	v_pk_add_f32 v[90:91], v[90:91], v[122:123]
	s_waitcnt vmcnt(5)
	v_pk_add_f32 v[88:89], v[88:89], v[128:129]
	v_pk_add_f32 v[86:87], v[86:87], v[126:127]
	s_waitcnt vmcnt(4)
	v_pk_add_f32 v[120:121], v[84:85], v[132:133]
	v_pk_add_f32 v[118:119], v[82:83], v[130:131]
	global_store_dwordx4 v[136:137], v[94:97], off nt
	global_store_dwordx4 v[136:137], v[90:93], off offset:16 nt
	v_cvt_pk_bf16_f32 v82, v94, v95
	v_cvt_pk_bf16_f32 v83, v96, v97
	v_cvt_pk_bf16_f32 v84, v90, v91
	v_cvt_pk_bf16_f32 v85, v92, v93
	v_mul_f32_e32 v95, v95, v95
	v_mul_f32_e32 v97, v97, v97
	v_mul_f32_e32 v91, v91, v91
	v_mul_f32_e32 v93, v93, v93
	v_mul_f32_e32 v122, v87, v87
	v_mul_f32_e32 v123, v89, v89
	v_mul_f32_e32 v124, v119, v119
	v_mul_f32_e32 v125, v121, v121
	v_fmac_f32_e32 v95, v94, v94
	v_fmac_f32_e32 v97, v96, v96
	v_fmac_f32_e32 v91, v90, v90
	v_fmac_f32_e32 v93, v92, v92
	v_fmac_f32_e32 v122, v86, v86
	v_fmac_f32_e32 v123, v88, v88
	v_fmac_f32_e32 v124, v118, v118
	v_fmac_f32_e32 v125, v120, v120
	global_store_dwordx4 v[138:139], v[82:85], off
	global_store_dwordx4 v[136:137], v[86:89], off offset:512 nt
	global_store_dwordx4 v[136:137], v[118:121], off offset:528 nt
	v_add_f32_e32 v82, v95, v97
	v_add_f32_e32 v83, v91, v93
	v_add_f32_e32 v84, v122, v123
	v_add_f32_e32 v85, v124, v125
	v_add_f32_e32 v82, v82, v83
	v_add_f32_e32 v83, v84, v85
	v_add_f32_e32 v82, v82, v83
	ds_bpermute_b32 v83, v198, v82
	v_cvt_pk_bf16_f32 v84, v86, v87
	v_cvt_pk_bf16_f32 v85, v88, v89
	v_cvt_pk_bf16_f32 v86, v118, v119
	v_cvt_pk_bf16_f32 v87, v120, v121
	s_waitcnt lgkmcnt(0)
	v_add_f32_e32 v82, v82, v83
	ds_bpermute_b32 v83, v197, v82
	v_lshl_add_u64 v[88:89], v[134:135], 1, s[24:25]
	global_store_dwordx4 v[88:89], v[84:87], off
	s_and_saveexec_b64 s[16:17], s[2:3]
	s_cbranch_execz .LBB0_1754
	s_waitcnt lgkmcnt(0)
	v_add_f32_e32 v82, v82, v83
	ds_write_b32 v192, v82 offset:128

; #define LAS __attribute__((address_space(3)))
;     DEVI f32x4 load(int r, int c) const { const bf16x4 y = *(const bf16x4*)(Y + (size_t)r * DM + c); return (f32x4){bf2f((u16)y[0]), bf2f((u16)y[1]), bf2f((u16)y[2]), bf2f((u16)y[3])}; }
; template <class Epi>
; DEVI void gemm_phase(LAS unsigned char* lds, const Gemm g, const Epi& E) {
;     ...
;             for (int am = 0; am < 4; ++am) {
;                 const int ai = am >> 1, m0 = (am & 1) * 2;
;                 f32x4 pre[2][2][2];
;                 if constexpr (Epi::PRE) {
; #pragma unroll
;                     for (int m = 0; m < 2; ++m)
; #pragma unroll
;                         for (int bj = 0; bj < 2; ++bj)
; #pragma unroll
;                             for (int n = 0; n < 2; ++n) pre[m][bj][n] = E.load(row0 + ai * HALF + (m0 + m) * 16, col0 + bj * HALF + n * NST);
;                 }
; #pragma unroll
;                 for (int mm = 0; mm < 2; ++mm) {
;                     const int m = m0 + mm;
;                     const int r = row0 + ai * HALF + m * 16; float rs = 1.f, part = 0.f;
;                     if constexpr (Epi::RS) rs = rsv[ai * 4 + m];
;                     if constexpr (Epi::PAIR) E.pair8(cur.b, r, cur.pn * HALF + wc * 32 + 8 * fq, acc[ai][0][m][0] * rs, acc[ai][0][m][1] * rs, acc[ai][1][m][0] * rs, acc[ai][1][m][1] * rs);
;                     else
; #pragma unroll
;                     for (int bj = 0; bj < 2; ++bj) {
;                         const int c = col0 + bj * HALF; f32x4 v0 = acc[ai][bj][m][0], v1 = acc[ai][bj][m][1];
;                         if constexpr (Epi::RS) { v0 = v0 * rs; v1 = v1 * rs; }
;                         if constexpr (Epi::PRE) part += E.frag_pre8(cur.b, r, c, v0, v1, pre[mm][bj][0], pre[mm][bj][1]);
;                         else if constexpr (Epi::PERM) E.frag8(cur.b, r, c, v0, v1);
;                         else { E.frag(cur.b, r, c, v0); E.frag(cur.b, r, c + 16, v1); }
;                     }
;                     if constexpr (Epi::SSQ) { part += __shfl_xor(part, 16); part += __shfl_xor(part, 32); if (fq == 0) ((LAS float*)(lds + 131072))[(wr * 4 + wc) * 128 + ai * 64 + m * 16 + fr] = part; }
.LBB0_1756:
	s_or_b64 exec, exec, s[16:17]
	v_add_u32_e32 v102, 0x80, v182
	v_ashrrev_i32_e32 v103, 31, v102
	s_waitcnt lgkmcnt(0)
	v_lshlrev_b64 v[66:67], 12, v[102:103]
	v_lshl_add_u64 v[66:67], s[30:31], 0, v[66:67]
	v_lshl_add_u64 v[104:105], v[66:67], 0, v[184:185]
	global_load_dwordx4 v[86:89], v[104:105], off nt
	global_load_dwordx4 v[90:93], v[104:105], off offset:16 nt
	global_load_dwordx4 v[94:97], v[104:105], off offset:512 nt
	global_load_dwordx4 v[98:101], v[104:105], off offset:528 nt
	v_add_u32_e32 v84, 0x90, v182
	v_ashrrev_i32_e32 v85, 31, v84
	v_lshlrev_b64 v[66:67], 12, v[84:85]
	v_lshl_add_u64 v[66:67], s[30:31], 0, v[66:67]
	v_lshl_add_u64 v[82:83], v[66:67], 0, v[184:185]
	global_load_dwordx4 v[74:77], v[82:83], off offset:16
	global_load_dwordx4 v[78:81], v[82:83], off
	global_load_dwordx4 v[66:69], v[82:83], off offset:528
	global_load_dwordx4 v[70:73], v[82:83], off offset:512
	v_lshlrev_b64 v[102:103], 10, v[102:103]
	v_lshl_add_u64 v[106:107], v[102:103], 0, v[180:181]
	v_lshl_add_u64 v[106:107], v[106:107], 1, s[24:25]
	v_lshl_add_u64 v[102:103], v[102:103], 0, v[178:179]
	s_waitcnt vmcnt(7)
	v_pk_add_f32 v[64:65], v[64:65], v[88:89]
	v_pk_add_f32 v[62:63], v[62:63], v[86:87]
	s_waitcnt vmcnt(6)
	v_pk_add_f32 v[60:61], v[60:61], v[92:93]
	v_pk_add_f32 v[58:59], v[58:59], v[90:91]
	s_waitcnt vmcnt(5)
	v_pk_add_f32 v[56:57], v[56:57], v[96:97]
	v_pk_add_f32 v[54:55], v[54:55], v[94:95]
	s_waitcnt vmcnt(4)
	v_pk_add_f32 v[88:89], v[52:53], v[100:101]
	v_pk_add_f32 v[86:87], v[50:51], v[98:99]
	global_store_dwordx4 v[104:105], v[62:65], off nt
	global_store_dwordx4 v[104:105], v[58:61], off offset:16 nt
	v_cvt_pk_bf16_f32 v50, v62, v63
	v_cvt_pk_bf16_f32 v51, v64, v65
	v_cvt_pk_bf16_f32 v52, v58, v59
	v_cvt_pk_bf16_f32 v53, v60, v61
	v_mul_f32_e32 v63, v63, v63
	v_mul_f32_e32 v65, v65, v65
	v_mul_f32_e32 v59, v59, v59
	v_mul_f32_e32 v61, v61, v61
	v_mul_f32_e32 v90, v55, v55
	v_mul_f32_e32 v91, v57, v57
	v_mul_f32_e32 v92, v87, v87
	v_mul_f32_e32 v93, v89, v89
	v_fmac_f32_e32 v63, v62, v62
	v_fmac_f32_e32 v65, v64, v64
	v_fmac_f32_e32 v59, v58, v58
	v_fmac_f32_e32 v61, v60, v60
	v_fmac_f32_e32 v90, v54, v54
	v_fmac_f32_e32 v91, v56, v56
	v_fmac_f32_e32 v92, v86, v86
	v_fmac_f32_e32 v93, v88, v88
	global_store_dwordx4 v[106:107], v[50:53], off
	global_store_dwordx4 v[104:105], v[54:57], off offset:512 nt
	global_store_dwordx4 v[104:105], v[86:89], off offset:528 nt
	v_add_f32_e32 v50, v63, v65
	v_add_f32_e32 v51, v59, v61
	v_add_f32_e32 v52, v90, v91
	v_add_f32_e32 v53, v92, v93
	v_add_f32_e32 v50, v50, v51
	v_add_f32_e32 v51, v52, v53
	v_add_f32_e32 v50, v50, v51
	ds_bpermute_b32 v51, v198, v50
	v_cvt_pk_bf16_f32 v52, v54, v55
	v_cvt_pk_bf16_f32 v53, v56, v57
	v_cvt_pk_bf16_f32 v54, v86, v87
	v_cvt_pk_bf16_f32 v55, v88, v89
	s_waitcnt lgkmcnt(0)
	v_add_f32_e32 v50, v50, v51
	ds_bpermute_b32 v51, v197, v50
	v_lshl_add_u64 v[56:57], v[102:103], 1, s[24:25]
	global_store_dwordx4 v[56:57], v[52:55], off
	s_and_saveexec_b64 s[16:17], s[2:3]
	s_cbranch_execz .LBB0_1758
	s_waitcnt lgkmcnt(0)
	v_add_f32_e32 v50, v50, v51
	ds_write_b32 v192, v50 offset:256

; #define LAS __attribute__((address_space(3)))
;     DEVI f32x4 load(int r, int c) const { const bf16x4 y = *(const bf16x4*)(Y + (size_t)r * DM + c); return (f32x4){bf2f((u16)y[0]), bf2f((u16)y[1]), bf2f((u16)y[2]), bf2f((u16)y[3])}; }
; template <class Epi>
; DEVI void gemm_phase(LAS unsigned char* lds, const Gemm g, const Epi& E) {
;     ...
;             for (int am = 0; am < 4; ++am) {
;                 const int ai = am >> 1, m0 = (am & 1) * 2;
;                 f32x4 pre[2][2][2];
;                 if constexpr (Epi::PRE) {
; #pragma unroll
;                     for (int m = 0; m < 2; ++m)
; #pragma unroll
;                         for (int bj = 0; bj < 2; ++bj)
; #pragma unroll
;                             for (int n = 0; n < 2; ++n) pre[m][bj][n] = E.load(row0 + ai * HALF + (m0 + m) * 16, col0 + bj * HALF + n * NST);
;                 }
; #pragma unroll
;                 for (int mm = 0; mm < 2; ++mm) {
;                     const int m = m0 + mm;
;                     const int r = row0 + ai * HALF + m * 16; float rs = 1.f, part = 0.f;
;                     if constexpr (Epi::RS) rs = rsv[ai * 4 + m];
;                     if constexpr (Epi::PAIR) E.pair8(cur.b, r, cur.pn * HALF + wc * 32 + 8 * fq, acc[ai][0][m][0] * rs, acc[ai][0][m][1] * rs, acc[ai][1][m][0] * rs, acc[ai][1][m][1] * rs);
;                     else
; #pragma unroll
;                     for (int bj = 0; bj < 2; ++bj) {
;                         const int c = col0 + bj * HALF; f32x4 v0 = acc[ai][bj][m][0], v1 = acc[ai][bj][m][1];
;                         if constexpr (Epi::RS) { v0 = v0 * rs; v1 = v1 * rs; }
;                         if constexpr (Epi::PRE) part += E.frag_pre8(cur.b, r, c, v0, v1, pre[mm][bj][0], pre[mm][bj][1]);
;                         else if constexpr (Epi::PERM) E.frag8(cur.b, r, c, v0, v1);
;                         else { E.frag(cur.b, r, c, v0); E.frag(cur.b, r, c + 16, v1); }
;                     }
;                     if constexpr (Epi::SSQ) { part += __shfl_xor(part, 16); part += __shfl_xor(part, 32); if (fq == 0) ((LAS float*)(lds + 131072))[(wr * 4 + wc) * 128 + ai * 64 + m * 16 + fr] = part; }
.LBB0_1760:
	s_or_b64 exec, exec, s[16:17]
	v_add_u32_e32 v70, 0xa0, v182
	v_ashrrev_i32_e32 v71, 31, v70
	s_waitcnt lgkmcnt(0)
	v_lshlrev_b64 v[34:35], 12, v[70:71]
	v_lshl_add_u64 v[34:35], s[30:31], 0, v[34:35]
	v_lshl_add_u64 v[72:73], v[34:35], 0, v[184:185]
	global_load_dwordx4 v[54:57], v[72:73], off nt
	global_load_dwordx4 v[58:61], v[72:73], off offset:16 nt
	global_load_dwordx4 v[62:65], v[72:73], off offset:512 nt
	global_load_dwordx4 v[66:69], v[72:73], off offset:528 nt
	v_add_u32_e32 v52, 0xb0, v182
	v_ashrrev_i32_e32 v53, 31, v52
	v_lshlrev_b64 v[34:35], 12, v[52:53]
	v_lshl_add_u64 v[34:35], s[30:31], 0, v[34:35]
	v_lshl_add_u64 v[50:51], v[34:35], 0, v[184:185]
	global_load_dwordx4 v[42:45], v[50:51], off offset:16
	global_load_dwordx4 v[46:49], v[50:51], off
	global_load_dwordx4 v[34:37], v[50:51], off offset:528
	global_load_dwordx4 v[38:41], v[50:51], off offset:512
	v_lshlrev_b64 v[70:71], 10, v[70:71]
	v_lshl_add_u64 v[74:75], v[70:71], 0, v[180:181]
	v_lshl_add_u64 v[74:75], v[74:75], 1, s[24:25]
	v_lshl_add_u64 v[70:71], v[70:71], 0, v[178:179]
	s_waitcnt vmcnt(7)
	v_pk_add_f32 v[32:33], v[32:33], v[56:57]
	v_pk_add_f32 v[30:31], v[30:31], v[54:55]
	s_waitcnt vmcnt(6)
	v_pk_add_f32 v[28:29], v[28:29], v[60:61]
	v_pk_add_f32 v[26:27], v[26:27], v[58:59]
	s_waitcnt vmcnt(5)
	v_pk_add_f32 v[24:25], v[24:25], v[64:65]
	v_pk_add_f32 v[22:23], v[22:23], v[62:63]
	s_waitcnt vmcnt(4)
	v_pk_add_f32 v[56:57], v[20:21], v[68:69]
	v_pk_add_f32 v[54:55], v[18:19], v[66:67]
	global_store_dwordx4 v[72:73], v[30:33], off nt
	global_store_dwordx4 v[72:73], v[26:29], off offset:16 nt
	v_cvt_pk_bf16_f32 v18, v30, v31
	v_cvt_pk_bf16_f32 v19, v32, v33
	v_cvt_pk_bf16_f32 v20, v26, v27
	v_cvt_pk_bf16_f32 v21, v28, v29
	v_mul_f32_e32 v31, v31, v31
	v_mul_f32_e32 v33, v33, v33
	v_mul_f32_e32 v27, v27, v27
	v_mul_f32_e32 v29, v29, v29
	v_mul_f32_e32 v58, v23, v23
	v_mul_f32_e32 v59, v25, v25
	v_mul_f32_e32 v60, v55, v55
	v_mul_f32_e32 v61, v57, v57
	v_fmac_f32_e32 v31, v30, v30
	v_fmac_f32_e32 v33, v32, v32
	v_fmac_f32_e32 v27, v26, v26
	v_fmac_f32_e32 v29, v28, v28
	v_fmac_f32_e32 v58, v22, v22
	v_fmac_f32_e32 v59, v24, v24
	v_fmac_f32_e32 v60, v54, v54
	v_fmac_f32_e32 v61, v56, v56
	global_store_dwordx4 v[74:75], v[18:21], off
	global_store_dwordx4 v[72:73], v[22:25], off offset:512 nt
	global_store_dwordx4 v[72:73], v[54:57], off offset:528 nt
	v_add_f32_e32 v18, v31, v33
	v_add_f32_e32 v19, v27, v29
	v_add_f32_e32 v20, v58, v59
	v_add_f32_e32 v21, v60, v61
	v_add_f32_e32 v18, v18, v19
	v_add_f32_e32 v19, v20, v21
	v_add_f32_e32 v18, v18, v19
	ds_bpermute_b32 v19, v198, v18
	v_cvt_pk_bf16_f32 v20, v22, v23
	v_cvt_pk_bf16_f32 v21, v24, v25
	v_cvt_pk_bf16_f32 v22, v54, v55
	v_cvt_pk_bf16_f32 v23, v56, v57
	s_waitcnt lgkmcnt(0)
	v_add_f32_e32 v18, v18, v19
	ds_bpermute_b32 v19, v197, v18
	v_lshl_add_u64 v[24:25], v[70:71], 1, s[24:25]
	global_store_dwordx4 v[24:25], v[20:23], off
	s_and_saveexec_b64 s[16:17], s[2:3]
	s_cbranch_execz .LBB0_1762
	s_waitcnt lgkmcnt(0)
	v_add_f32_e32 v18, v18, v19
	ds_write_b32 v192, v18 offset:384
